# ordering check: B-fragment LDS reads issued before the A-fragment reads in the 16-read load segments
# baseline (speedup 1.0000x reference)
; #define PG8_STAGE(bufoff, gbase, voff) do { _Pragma("unroll") for (int _i = 0; _i < 2; ++_i) \
;         __builtin_amdgcn_global_load_lds((const unsigned*)((const char*)(gbase) + (voff)[_i]), (PG8_LAS unsigned*)(lds + (bufoff) + ldsw + _i * 8192), 16, 0, 0); } while (0)
; #define PG8_LDA(dst, b, h) do { _Pragma("unroll") for (int m = 0; m < 4; ++m) _Pragma("unroll") for (int k = 0; k < 2; ++k) dst[m][k] = *(const PG8_LAS bf16x8*)(lds + PG8_SA(b, h) + aoff + m * 2048 + k * 1024); } while (0)
; #define PG8_LDB(dst, b, h) do { _Pragma("unroll") for (int n = 0; n < 2; ++n) _Pragma("unroll") for (int k = 0; k < 2; ++k) dst[n][k] = *(const PG8_LAS bf16x8*)(lds + PG8_SB(b, h) + boff + n * 2048 + k * 1024); } while (0)
; #define PG8_MMA(ai, bj, At, Bt) do { __builtin_amdgcn_s_setprio(1); _Pragma("unroll") for (int m = 0; m < 4; ++m) _Pragma("unroll") for (int n = 0; n < 2; ++n) _Pragma("unroll") for (int k = 0; k < 2; ++k) \
;         acc[ai][bj][m][n] = __builtin_amdgcn_mfma_f32_16x16x32_bf16(Bt[n][k], At[m][k], acc[ai][bj][m][n], 0, 0, 0); __builtin_amdgcn_s_setprio(0); } while (0)
; #define PG8_WAIT_V(n) asm volatile("s_waitcnt vmcnt(" #n ")" ::: "memory")
; #define PG8_WAIT_L(n) asm volatile("s_waitcnt lgkmcnt(" #n ")" ::: "memory")
; #define PG8_BAR __builtin_amdgcn_s_barrier()
; #define PG8_SCHED __builtin_amdgcn_sched_barrier(0)
; template <class Epi, class Sched, bool ALIGN_EPI = false, bool SP2 = false>
; __device__ __forceinline__ void gemm_phase(PG8_LAS unsigned char* lds, const Gemm g, const Sched& S, const Epi& E) {
;     ...
;             PG8_LDB(B0, 0, 0); PG8_LDB(B1, 0, 1); PG8_SCHED; PG8_LDA(At, 0, 0); PG8_STAGE(PG8_SA(1, 1), a1 + hstep, voffA);
;             PG8_WAIT_V(8); PG8_WAIT_L(0); PG8_BAR; PG8_MMA(0, 0, At, B0); PG8_MMA(0, 1, At, B1); PG8_BAR; PG8_SCHED;
;             PG8_LDA(At, 0, 1); PG8_STAGE(PG8_SB(0, 0), b2, voffB); PG8_STAGE(PG8_SB(0, 1), b2 + hstep, voffB); PG8_STAGE(PG8_SA(0, 0), a2, voffA);
;             PG8_WAIT_V(8); PG8_WAIT_L(0); PG8_BAR; PG8_MMA(1, 0, At, B0); PG8_MMA(1, 1, At, B1); PG8_BAR; PG8_SCHED;
.LBB0_132:
	s_add_u32 s18, s46, 0xfffc0080
	s_addc_u32 s38, s47, -1
	s_add_i32 s39, 0, 0x10000
	s_cmp_eq_u32 s85, 12
	s_cselect_b32 s81, s33, s38
	s_cselect_b32 s80, s73, s18
	v_add_u32_e32 v0, s39, v176
	s_cselect_b32 s45, s75, s84
	s_cselect_b32 s44, s82, s83
	s_add_i32 s18, 0, 0x14000
	ds_read_b128 v[180:183], v178
	ds_read_b128 v[184:187], v178 offset:1024
	ds_read_b128 v[188:191], v178 offset:2048
	ds_read_b128 v[192:195], v178 offset:3072
	ds_read_b128 v[202:205], v178 offset:4096
	ds_read_b128 v[206:209], v178 offset:5120
	ds_read_b128 v[210:213], v178 offset:6144
	ds_read_b128 v[214:217], v178 offset:7168
	ds_read_b128 v[144:147], v0
	ds_read_b128 v[148:151], v0 offset:1024
	ds_read_b128 v[152:155], v0 offset:2048
	ds_read_b128 v[156:159], v0 offset:3072
	v_add_u32_e32 v0, s18, v176
	ds_read_b128 v[160:163], v0
	ds_read_b128 v[164:167], v0 offset:1024
	ds_read_b128 v[168:171], v0 offset:2048
	ds_read_b128 v[172:175], v0 offset:3072
	v_lshl_add_u64 v[218:219], s[46:47], 0, v[140:141]
	s_add_i32 m0, s92, 0xc000
	global_load_lds_dwordx4 v[218:219], off
	v_lshl_add_u64 v[218:219], s[46:47], 0, v[142:143]
	s_add_i32 m0, s92, 0xe000
	s_nop 0
	global_load_lds_dwordx4 v[218:219], off
	s_waitcnt vmcnt(8)
	s_waitcnt lgkmcnt(0)
	s_barrier
	s_setprio 1
	v_mfma_f32_16x16x32_bf16 v[118:121], v[144:147], v[180:183], v[118:121]
	v_mfma_f32_16x16x32_bf16 v[118:121], v[148:151], v[184:187], v[118:121]
	v_mfma_f32_16x16x32_bf16 v[102:105], v[144:147], v[188:191], v[102:105]
	v_mfma_f32_16x16x32_bf16 v[102:105], v[148:151], v[192:195], v[102:105]
	v_mfma_f32_16x16x32_bf16 v[86:89], v[144:147], v[202:205], v[86:89]
	v_mfma_f32_16x16x32_bf16 v[86:89], v[148:151], v[206:209], v[86:89]
	v_mfma_f32_16x16x32_bf16 v[70:73], v[144:147], v[210:213], v[70:73]
	v_mfma_f32_16x16x32_bf16 v[70:73], v[148:151], v[214:217], v[70:73]
	v_mfma_f32_16x16x32_bf16 v[114:117], v[152:155], v[180:183], v[114:117]
	v_mfma_f32_16x16x32_bf16 v[114:117], v[156:159], v[184:187], v[114:117]
	v_mfma_f32_16x16x32_bf16 v[98:101], v[152:155], v[188:191], v[98:101]
	v_mfma_f32_16x16x32_bf16 v[98:101], v[156:159], v[192:195], v[98:101]
	v_mfma_f32_16x16x32_bf16 v[82:85], v[152:155], v[202:205], v[82:85]
	v_mfma_f32_16x16x32_bf16 v[82:85], v[156:159], v[206:209], v[82:85]
	v_mfma_f32_16x16x32_bf16 v[66:69], v[152:155], v[210:213], v[66:69]
	v_mfma_f32_16x16x32_bf16 v[66:69], v[156:159], v[214:217], v[66:69]
	v_mfma_f32_16x16x32_bf16 v[126:129], v[160:163], v[180:183], v[126:129]
	v_mfma_f32_16x16x32_bf16 v[126:129], v[164:167], v[184:187], v[126:129]
	v_mfma_f32_16x16x32_bf16 v[110:113], v[160:163], v[188:191], v[110:113]
	v_mfma_f32_16x16x32_bf16 v[110:113], v[164:167], v[192:195], v[110:113]
	v_mfma_f32_16x16x32_bf16 v[94:97], v[160:163], v[202:205], v[94:97]
	v_mfma_f32_16x16x32_bf16 v[94:97], v[164:167], v[206:209], v[94:97]
	v_mfma_f32_16x16x32_bf16 v[78:81], v[160:163], v[210:213], v[78:81]
	v_mfma_f32_16x16x32_bf16 v[78:81], v[164:167], v[214:217], v[78:81]
	v_mfma_f32_16x16x32_bf16 v[122:125], v[168:171], v[180:183], v[122:125]
	v_mfma_f32_16x16x32_bf16 v[122:125], v[172:175], v[184:187], v[122:125]
	v_mfma_f32_16x16x32_bf16 v[106:109], v[168:171], v[188:191], v[106:109]
	v_mfma_f32_16x16x32_bf16 v[106:109], v[172:175], v[192:195], v[106:109]
	v_mfma_f32_16x16x32_bf16 v[90:93], v[168:171], v[202:205], v[90:93]
	v_mfma_f32_16x16x32_bf16 v[90:93], v[172:175], v[206:209], v[90:93]
	v_mfma_f32_16x16x32_bf16 v[74:77], v[168:171], v[210:213], v[74:77]
	v_mfma_f32_16x16x32_bf16 v[74:77], v[172:175], v[214:217], v[74:77]
	s_setprio 0
	s_barrier
	s_add_i32 s38, s39, s91
	v_lshl_add_u64 v[218:219], s[44:45], 0, v[134:135]
	s_mov_b32 m0, s38
	ds_read_b128 v[180:183], v178 offset:16384
	ds_read_b128 v[184:187], v178 offset:17408
	ds_read_b128 v[188:191], v178 offset:18432
	ds_read_b128 v[192:195], v178 offset:19456
	ds_read_b128 v[202:205], v178 offset:20480
	ds_read_b128 v[206:209], v178 offset:21504
	ds_read_b128 v[210:213], v178 offset:22528
	ds_read_b128 v[214:217], v178 offset:23552
	global_load_lds_dwordx4 v[218:219], off
	s_add_i32 m0, s38, 0x2000
	s_add_u32 s38, s44, 0x40000
	v_lshl_add_u64 v[220:221], s[44:45], 0, v[130:131]
	s_addc_u32 s39, s45, 0
	s_add_i32 s18, s18, s91
	global_load_lds_dwordx4 v[220:221], off
	v_lshl_add_u64 v[222:223], s[38:39], 0, v[134:135]
	s_mov_b32 m0, s18
	v_lshl_add_u64 v[224:225], s[80:81], 0, v[132:133]
	global_load_lds_dwordx4 v[222:223], off
	v_lshl_add_u64 v[222:223], s[38:39], 0, v[130:131]
	s_add_i32 m0, s18, 0x2000
	s_nop 0
	global_load_lds_dwordx4 v[222:223], off
	v_lshl_add_u64 v[222:223], s[80:81], 0, v[136:137]
	s_mov_b32 m0, s92
	s_nop 0
	global_load_lds_dwordx4 v[222:223], off
	s_mov_b32 m0, s93
	s_nop 0
	global_load_lds_dwordx4 v[224:225], off
	s_waitcnt vmcnt(8)
	s_waitcnt lgkmcnt(0)
	s_barrier
; #define PG8_STAGE(bufoff, gbase, voff) do { _Pragma("unroll") for (int _i = 0; _i < 2; ++_i) \
;         __builtin_amdgcn_global_load_lds((const unsigned*)((const char*)(gbase) + (voff)[_i]), (PG8_LAS unsigned*)(lds + (bufoff) + ldsw + _i * 8192), 16, 0, 0); } while (0)
; #define PG8_LDA(dst, b, h) do { _Pragma("unroll") for (int m = 0; m < 4; ++m) _Pragma("unroll") for (int k = 0; k < 2; ++k) dst[m][k] = *(const PG8_LAS bf16x8*)(lds + PG8_SA(b, h) + aoff + m * 2048 + k * 1024); } while (0)
; #define PG8_LDB(dst, b, h) do { _Pragma("unroll") for (int n = 0; n < 2; ++n) _Pragma("unroll") for (int k = 0; k < 2; ++k) dst[n][k] = *(const PG8_LAS bf16x8*)(lds + PG8_SB(b, h) + boff + n * 2048 + k * 1024); } while (0)
; #define PG8_MMA(ai, bj, At, Bt) do { __builtin_amdgcn_s_setprio(1); _Pragma("unroll") for (int m = 0; m < 4; ++m) _Pragma("unroll") for (int n = 0; n < 2; ++n) _Pragma("unroll") for (int k = 0; k < 2; ++k) \
;         acc[ai][bj][m][n] = __builtin_amdgcn_mfma_f32_16x16x32_bf16(Bt[n][k], At[m][k], acc[ai][bj][m][n], 0, 0, 0); __builtin_amdgcn_s_setprio(0); } while (0)
; #define PG8_WAIT_V(n) asm volatile("s_waitcnt vmcnt(" #n ")" ::: "memory")
; #define PG8_WAIT_L(n) asm volatile("s_waitcnt lgkmcnt(" #n ")" ::: "memory")
; #define PG8_BAR __builtin_amdgcn_s_barrier()
; #define PG8_SCHED __builtin_amdgcn_sched_barrier(0)
; template <class Epi, class Sched, bool ALIGN_EPI = false, bool SP2 = false>
; __device__ __forceinline__ void gemm_phase(PG8_LAS unsigned char* lds, const Gemm g, const Sched& S, const Epi& E) {
;     ...
;             PG8_WAIT_V(8); PG8_WAIT_L(0); PG8_BAR; PG8_MMA(1, 0, At, B0); PG8_MMA(1, 1, At, B1); PG8_BAR; PG8_SCHED;
;             PG8_LDB(B0, 1, 0); PG8_LDB(B1, 1, 1); PG8_SCHED; PG8_LDA(At, 1, 0); PG8_STAGE(PG8_SA(0, 1), a2 + hstep, voffA);
;             PG8_WAIT_V(8); PG8_WAIT_L(0); PG8_BAR; PG8_MMA(0, 0, At, B0); PG8_MMA(0, 1, At, B1); PG8_BAR; PG8_SCHED;
	s_setprio 1
	v_mfma_f32_16x16x32_bf16 v[54:57], v[144:147], v[180:183], v[54:57]
	v_mfma_f32_16x16x32_bf16 v[54:57], v[148:151], v[184:187], v[54:57]
	v_mfma_f32_16x16x32_bf16 v[38:41], v[144:147], v[188:191], v[38:41]
	v_mfma_f32_16x16x32_bf16 v[38:41], v[148:151], v[192:195], v[38:41]
	v_mfma_f32_16x16x32_bf16 v[22:25], v[144:147], v[202:205], v[22:25]
	v_mfma_f32_16x16x32_bf16 v[22:25], v[148:151], v[206:209], v[22:25]
	v_mfma_f32_16x16x32_bf16 v[6:9], v[144:147], v[210:213], v[6:9]
	v_mfma_f32_16x16x32_bf16 v[6:9], v[148:151], v[214:217], v[6:9]
	v_mfma_f32_16x16x32_bf16 v[50:53], v[152:155], v[180:183], v[50:53]
	v_mfma_f32_16x16x32_bf16 v[50:53], v[156:159], v[184:187], v[50:53]
	v_mfma_f32_16x16x32_bf16 v[34:37], v[152:155], v[188:191], v[34:37]
	v_mfma_f32_16x16x32_bf16 v[34:37], v[156:159], v[192:195], v[34:37]
	v_mfma_f32_16x16x32_bf16 v[18:21], v[152:155], v[202:205], v[18:21]
	v_mfma_f32_16x16x32_bf16 v[18:21], v[156:159], v[206:209], v[18:21]
	v_mfma_f32_16x16x32_bf16 v[2:5], v[152:155], v[210:213], v[2:5]
	v_mfma_f32_16x16x32_bf16 v[2:5], v[156:159], v[214:217], v[2:5]
	v_mfma_f32_16x16x32_bf16 v[62:65], v[160:163], v[180:183], v[62:65]
	v_mfma_f32_16x16x32_bf16 v[62:65], v[164:167], v[184:187], v[62:65]
	v_mfma_f32_16x16x32_bf16 v[46:49], v[160:163], v[188:191], v[46:49]
	v_mfma_f32_16x16x32_bf16 v[46:49], v[164:167], v[192:195], v[46:49]
	v_mfma_f32_16x16x32_bf16 v[30:33], v[160:163], v[202:205], v[30:33]
	v_mfma_f32_16x16x32_bf16 v[30:33], v[164:167], v[206:209], v[30:33]
	v_mfma_f32_16x16x32_bf16 v[10:13], v[160:163], v[210:213], v[10:13]
	v_mfma_f32_16x16x32_bf16 v[10:13], v[164:167], v[214:217], v[10:13]
	v_mfma_f32_16x16x32_bf16 v[58:61], v[168:171], v[180:183], v[58:61]
	v_mfma_f32_16x16x32_bf16 v[58:61], v[172:175], v[184:187], v[58:61]
	v_mfma_f32_16x16x32_bf16 v[42:45], v[168:171], v[188:191], v[42:45]
	v_mfma_f32_16x16x32_bf16 v[42:45], v[172:175], v[192:195], v[42:45]
	v_mfma_f32_16x16x32_bf16 v[26:29], v[168:171], v[202:205], v[26:29]
	v_mfma_f32_16x16x32_bf16 v[26:29], v[172:175], v[206:209], v[26:29]
	v_mfma_f32_16x16x32_bf16 v[14:17], v[168:171], v[210:213], v[14:17]
	v_mfma_f32_16x16x32_bf16 v[14:17], v[172:175], v[214:217], v[14:17]
	s_setprio 0
	s_barrier
	s_add_i32 s18, 0, 0x18000
	v_add_u32_e32 v0, s18, v176
	s_add_i32 vcc_lo, 0, 0x1c000
	ds_read_b128 v[180:183], v178 offset:32768
	ds_read_b128 v[184:187], v178 offset:33792
	ds_read_b128 v[188:191], v178 offset:34816
	ds_read_b128 v[192:195], v178 offset:35840
	ds_read_b128 v[202:205], v178 offset:36864
	ds_read_b128 v[206:209], v178 offset:37888
	ds_read_b128 v[210:213], v178 offset:38912
	ds_read_b128 v[214:217], v178 offset:39936
	ds_read_b128 v[144:147], v0
	ds_read_b128 v[148:151], v0 offset:1024
	ds_read_b128 v[152:155], v0 offset:2048
	ds_read_b128 v[156:159], v0 offset:3072
	v_add_u32_e32 v0, vcc_lo, v176
	ds_read_b128 v[160:163], v0
	ds_read_b128 v[164:167], v0 offset:1024
	ds_read_b128 v[168:171], v0 offset:2048
	ds_read_b128 v[172:175], v0 offset:3072
	s_add_u32 s38, s80, 0x40000
	s_addc_u32 s39, s81, 0
	s_mov_b32 m0, s94
	v_lshl_add_u64 v[226:227], s[38:39], 0, v[136:137]
	global_load_lds_dwordx4 v[226:227], off
	v_lshl_add_u64 v[226:227], s[38:39], 0, v[132:133]
	s_mov_b32 m0, s95
	s_nop 0
	global_load_lds_dwordx4 v[226:227], off
	s_waitcnt vmcnt(8)
	s_waitcnt lgkmcnt(0)
	s_barrier
	s_setprio 1
	v_mfma_f32_16x16x32_bf16 v[118:121], v[144:147], v[180:183], v[118:121]
	v_mfma_f32_16x16x32_bf16 v[118:121], v[148:151], v[184:187], v[118:121]
	v_mfma_f32_16x16x32_bf16 v[102:105], v[144:147], v[188:191], v[102:105]
	v_mfma_f32_16x16x32_bf16 v[102:105], v[148:151], v[192:195], v[102:105]
	v_mfma_f32_16x16x32_bf16 v[86:89], v[144:147], v[202:205], v[86:89]
	v_mfma_f32_16x16x32_bf16 v[86:89], v[148:151], v[206:209], v[86:89]
	v_mfma_f32_16x16x32_bf16 v[70:73], v[144:147], v[210:213], v[70:73]
	v_mfma_f32_16x16x32_bf16 v[70:73], v[148:151], v[214:217], v[70:73]
	v_mfma_f32_16x16x32_bf16 v[114:117], v[152:155], v[180:183], v[114:117]
	v_mfma_f32_16x16x32_bf16 v[114:117], v[156:159], v[184:187], v[114:117]
	v_mfma_f32_16x16x32_bf16 v[98:101], v[152:155], v[188:191], v[98:101]
	v_mfma_f32_16x16x32_bf16 v[98:101], v[156:159], v[192:195], v[98:101]
	v_mfma_f32_16x16x32_bf16 v[82:85], v[152:155], v[202:205], v[82:85]
	v_mfma_f32_16x16x32_bf16 v[82:85], v[156:159], v[206:209], v[82:85]
	v_mfma_f32_16x16x32_bf16 v[66:69], v[152:155], v[210:213], v[66:69]
	v_mfma_f32_16x16x32_bf16 v[66:69], v[156:159], v[214:217], v[66:69]
	v_mfma_f32_16x16x32_bf16 v[126:129], v[160:163], v[180:183], v[126:129]
	v_mfma_f32_16x16x32_bf16 v[126:129], v[164:167], v[184:187], v[126:129]
	v_mfma_f32_16x16x32_bf16 v[110:113], v[160:163], v[188:191], v[110:113]
	v_mfma_f32_16x16x32_bf16 v[110:113], v[164:167], v[192:195], v[110:113]
	v_mfma_f32_16x16x32_bf16 v[94:97], v[160:163], v[202:205], v[94:97]
	v_mfma_f32_16x16x32_bf16 v[94:97], v[164:167], v[206:209], v[94:97]
	v_mfma_f32_16x16x32_bf16 v[78:81], v[160:163], v[210:213], v[78:81]
	v_mfma_f32_16x16x32_bf16 v[78:81], v[164:167], v[214:217], v[78:81]
	v_mfma_f32_16x16x32_bf16 v[122:125], v[168:171], v[180:183], v[122:125]
	v_mfma_f32_16x16x32_bf16 v[122:125], v[172:175], v[184:187], v[122:125]
	v_mfma_f32_16x16x32_bf16 v[106:109], v[168:171], v[188:191], v[106:109]
	v_mfma_f32_16x16x32_bf16 v[106:109], v[172:175], v[192:195], v[106:109]
	v_mfma_f32_16x16x32_bf16 v[90:93], v[168:171], v[202:205], v[90:93]
	v_mfma_f32_16x16x32_bf16 v[90:93], v[172:175], v[206:209], v[90:93]
	v_mfma_f32_16x16x32_bf16 v[74:77], v[168:171], v[210:213], v[74:77]
	v_mfma_f32_16x16x32_bf16 v[74:77], v[172:175], v[214:217], v[74:77]
	s_setprio 0
	s_barrier
; #define PG8_STAGE(bufoff, gbase, voff) do { _Pragma("unroll") for (int _i = 0; _i < 2; ++_i) \
;         __builtin_amdgcn_global_load_lds((const unsigned*)((const char*)(gbase) + (voff)[_i]), (PG8_LAS unsigned*)(lds + (bufoff) + ldsw + _i * 8192), 16, 0, 0); } while (0)
; #define PG8_LDA(dst, b, h) do { _Pragma("unroll") for (int m = 0; m < 4; ++m) _Pragma("unroll") for (int k = 0; k < 2; ++k) dst[m][k] = *(const PG8_LAS bf16x8*)(lds + PG8_SA(b, h) + aoff + m * 2048 + k * 1024); } while (0)
; #define PG8_MMA(ai, bj, At, Bt) do { __builtin_amdgcn_s_setprio(1); _Pragma("unroll") for (int m = 0; m < 4; ++m) _Pragma("unroll") for (int n = 0; n < 2; ++n) _Pragma("unroll") for (int k = 0; k < 2; ++k) \
;         acc[ai][bj][m][n] = __builtin_amdgcn_mfma_f32_16x16x32_bf16(Bt[n][k], At[m][k], acc[ai][bj][m][n], 0, 0, 0); __builtin_amdgcn_s_setprio(0); } while (0)
; #define PG8_WAIT_V(n) asm volatile("s_waitcnt vmcnt(" #n ")" ::: "memory")
; #define PG8_WAIT_L(n) asm volatile("s_waitcnt lgkmcnt(" #n ")" ::: "memory")
; #define PG8_BAR __builtin_amdgcn_s_barrier()
; #define PG8_SCHED __builtin_amdgcn_sched_barrier(0)
; template <class Epi, class Sched, bool ALIGN_EPI = false, bool SP2 = false>
; __device__ __forceinline__ void gemm_phase(PG8_LAS unsigned char* lds, const Gemm g, const Sched& S, const Epi& E) {
;     ...
;         for (int t = 0; t < nt; t += 2) {
;             const bool last = (t == nt - 2);
;     ...
;             PG8_LDA(At, 1, 1); PG8_STAGE(PG8_SB(1, 0), b3, voffB); PG8_STAGE(PG8_SB(1, 1), b3 + hstep, voffB); PG8_STAGE(PG8_SA(1, 0), a3, voffA);
;             PG8_WAIT_V(8); PG8_WAIT_L(0); PG8_BAR; PG8_MMA(1, 0, At, B0); PG8_MMA(1, 1, At, B1); PG8_BAR; PG8_SCHED;
	s_add_i32 s18, s18, s91
	v_lshl_add_u64 v[218:219], v[218:219], 0, s[30:31]
	s_mov_b32 m0, s18
	ds_read_b128 v[180:183], v178 offset:49152
	ds_read_b128 v[184:187], v178 offset:50176
	ds_read_b128 v[188:191], v178 offset:51200
	ds_read_b128 v[192:195], v178 offset:52224
	ds_read_b128 v[202:205], v178 offset:53248
	ds_read_b128 v[206:209], v178 offset:54272
	ds_read_b128 v[210:213], v178 offset:55296
	ds_read_b128 v[214:217], v178 offset:56320
	global_load_lds_dwordx4 v[218:219], off
	s_add_i32 m0, s18, 0x2000
	s_add_u32 s38, s44, 0x40080
	v_lshl_add_u64 v[218:219], v[220:221], 0, s[30:31]
	s_addc_u32 s39, s45, 0
	s_add_i32 s18, vcc_lo, s91
	global_load_lds_dwordx4 v[218:219], off
	v_lshl_add_u64 v[218:219], s[38:39], 0, v[134:135]
	s_mov_b32 m0, s18
	s_nop 0
	global_load_lds_dwordx4 v[218:219], off
	v_lshl_add_u64 v[218:219], s[38:39], 0, v[130:131]
	s_add_i32 m0, s18, 0x2000
	s_nop 0
	global_load_lds_dwordx4 v[218:219], off
	v_lshl_add_u64 v[218:219], v[222:223], 0, s[30:31]
	s_mov_b32 m0, s7
	s_nop 0
	global_load_lds_dwordx4 v[218:219], off
	v_lshl_add_u64 v[218:219], v[224:225], 0, s[30:31]
	s_mov_b32 m0, s96
	s_nop 0
	global_load_lds_dwordx4 v[218:219], off
	s_waitcnt vmcnt(8)
	s_waitcnt lgkmcnt(0)
	s_barrier
	s_setprio 1
	v_mfma_f32_16x16x32_bf16 v[54:57], v[144:147], v[180:183], v[54:57]
	v_mfma_f32_16x16x32_bf16 v[54:57], v[148:151], v[184:187], v[54:57]
	v_mfma_f32_16x16x32_bf16 v[38:41], v[144:147], v[188:191], v[38:41]
	v_mfma_f32_16x16x32_bf16 v[38:41], v[148:151], v[192:195], v[38:41]
	v_mfma_f32_16x16x32_bf16 v[22:25], v[144:147], v[202:205], v[22:25]
	v_mfma_f32_16x16x32_bf16 v[22:25], v[148:151], v[206:209], v[22:25]
	v_mfma_f32_16x16x32_bf16 v[6:9], v[144:147], v[210:213], v[6:9]
	v_mfma_f32_16x16x32_bf16 v[6:9], v[148:151], v[214:217], v[6:9]
	v_mfma_f32_16x16x32_bf16 v[50:53], v[152:155], v[180:183], v[50:53]
	v_mfma_f32_16x16x32_bf16 v[50:53], v[156:159], v[184:187], v[50:53]
	v_mfma_f32_16x16x32_bf16 v[34:37], v[152:155], v[188:191], v[34:37]
	v_mfma_f32_16x16x32_bf16 v[34:37], v[156:159], v[192:195], v[34:37]
	v_mfma_f32_16x16x32_bf16 v[18:21], v[152:155], v[202:205], v[18:21]
	v_mfma_f32_16x16x32_bf16 v[18:21], v[156:159], v[206:209], v[18:21]
	v_mfma_f32_16x16x32_bf16 v[2:5], v[152:155], v[210:213], v[2:5]
	v_mfma_f32_16x16x32_bf16 v[2:5], v[156:159], v[214:217], v[2:5]
	v_mfma_f32_16x16x32_bf16 v[62:65], v[160:163], v[180:183], v[62:65]
	v_mfma_f32_16x16x32_bf16 v[62:65], v[164:167], v[184:187], v[62:65]
	v_mfma_f32_16x16x32_bf16 v[46:49], v[160:163], v[188:191], v[46:49]
	v_mfma_f32_16x16x32_bf16 v[46:49], v[164:167], v[192:195], v[46:49]
	v_mfma_f32_16x16x32_bf16 v[30:33], v[160:163], v[202:205], v[30:33]
	v_mfma_f32_16x16x32_bf16 v[30:33], v[164:167], v[206:209], v[30:33]
	v_mfma_f32_16x16x32_bf16 v[10:13], v[160:163], v[210:213], v[10:13]
	v_mfma_f32_16x16x32_bf16 v[10:13], v[164:167], v[214:217], v[10:13]
	v_mfma_f32_16x16x32_bf16 v[58:61], v[168:171], v[180:183], v[58:61]
	v_mfma_f32_16x16x32_bf16 v[58:61], v[172:175], v[184:187], v[58:61]
	v_mfma_f32_16x16x32_bf16 v[42:45], v[168:171], v[188:191], v[42:45]
	v_mfma_f32_16x16x32_bf16 v[42:45], v[172:175], v[192:195], v[42:45]
	v_mfma_f32_16x16x32_bf16 v[26:29], v[168:171], v[202:205], v[26:29]
	v_mfma_f32_16x16x32_bf16 v[26:29], v[172:175], v[206:209], v[26:29]
	v_mfma_f32_16x16x32_bf16 v[14:17], v[168:171], v[210:213], v[14:17]
	v_mfma_f32_16x16x32_bf16 v[14:17], v[172:175], v[214:217], v[14:17]
	s_setprio 0
	s_barrier
	s_add_i32 s85, s85, 2
	s_add_u32 s46, s46, 0x100
	s_addc_u32 s47, s47, 0
	s_add_u32 s83, s83, 0x100
	s_addc_u32 s84, s84, 0
	s_cmp_gt_u32 s85, 13
	s_cbranch_scc0 .LBB0_132
	s_and_b64 vcc, exec, s[10:11]
	s_cbranch_vccz .LBB0_135
	s_barrier

; #define PG8_STAGE(bufoff, gbase, voff) do { _Pragma("unroll") for (int _i = 0; _i < 2; ++_i) \
;         __builtin_amdgcn_global_load_lds((const unsigned*)((const char*)(gbase) + (voff)[_i]), (PG8_LAS unsigned*)(lds + (bufoff) + ldsw + _i * 8192), 16, 0, 0); } while (0)
; #define PG8_LDA(dst, b, h) do { _Pragma("unroll") for (int m = 0; m < 4; ++m) _Pragma("unroll") for (int k = 0; k < 2; ++k) dst[m][k] = *(const PG8_LAS bf16x8*)(lds + PG8_SA(b, h) + aoff + m * 2048 + k * 1024); } while (0)
; #define PG8_LDB(dst, b, h) do { _Pragma("unroll") for (int n = 0; n < 2; ++n) _Pragma("unroll") for (int k = 0; k < 2; ++k) dst[n][k] = *(const PG8_LAS bf16x8*)(lds + PG8_SB(b, h) + boff + n * 2048 + k * 1024); } while (0)
; #define PG8_MMA(ai, bj, At, Bt) do { __builtin_amdgcn_s_setprio(1); _Pragma("unroll") for (int m = 0; m < 4; ++m) _Pragma("unroll") for (int n = 0; n < 2; ++n) _Pragma("unroll") for (int k = 0; k < 2; ++k) \
;         acc[ai][bj][m][n] = __builtin_amdgcn_mfma_f32_16x16x32_bf16(Bt[n][k], At[m][k], acc[ai][bj][m][n], 0, 0, 0); __builtin_amdgcn_s_setprio(0); } while (0)
; #define PG8_WAIT_V(n) asm volatile("s_waitcnt vmcnt(" #n ")" ::: "memory")
; #define PG8_WAIT_L(n) asm volatile("s_waitcnt lgkmcnt(" #n ")" ::: "memory")
; #define PG8_BAR __builtin_amdgcn_s_barrier()
; #define PG8_SCHED __builtin_amdgcn_sched_barrier(0)
; template <class Epi, class Sched, bool ALIGN_EPI = false, bool SP2 = false>
; __device__ __forceinline__ void gemm_phase(PG8_LAS unsigned char* lds, const Gemm g, const Sched& S, const Epi& E) {
;     ...
;             PG8_LDB(B0, 0, 0); PG8_LDB(B1, 0, 1); PG8_SCHED; PG8_LDA(At, 0, 0); PG8_STAGE(PG8_SA(1, 1), a1 + hstep, voffA);
;             PG8_WAIT_V(8); PG8_WAIT_L(0); PG8_BAR; PG8_MMA(0, 0, At, B0); PG8_MMA(0, 1, At, B1); PG8_BAR; PG8_SCHED;
;             PG8_LDA(At, 0, 1); PG8_STAGE(PG8_SB(0, 0), b2, voffB); PG8_STAGE(PG8_SB(0, 1), b2 + hstep, voffB); PG8_STAGE(PG8_SA(0, 0), a2, voffA);
;             PG8_WAIT_V(8); PG8_WAIT_L(0); PG8_BAR; PG8_MMA(1, 0, At, B0); PG8_MMA(1, 1, At, B1); PG8_BAR; PG8_SCHED;
.LBB0_220:
	s_add_u32 s18, s60, 0xfffc0080
	s_addc_u32 s38, s61, -1
	s_add_i32 s39, 0, 0x10000
	s_cmp_eq_u32 s82, 12
	s_cselect_b32 s65, s47, s38
	s_cselect_b32 s64, s78, s18
	v_add_u32_e32 v145, s39, v141
	s_cselect_b32 s57, s49, s81
	s_cselect_b32 s56, s79, s80
	s_add_i32 s18, 0, 0x14000
	ds_read_b128 v[178:181], v144
	ds_read_b128 v[182:185], v144 offset:1024
	ds_read_b128 v[186:189], v144 offset:2048
	ds_read_b128 v[190:193], v144 offset:3072
	ds_read_b128 v[202:205], v144 offset:4096
	ds_read_b128 v[206:209], v144 offset:5120
	ds_read_b128 v[210:213], v144 offset:6144
	ds_read_b128 v[214:217], v144 offset:7168
	ds_read_b128 v[146:149], v145
	ds_read_b128 v[150:153], v145 offset:1024
	ds_read_b128 v[154:157], v145 offset:2048
	ds_read_b128 v[158:161], v145 offset:3072
	v_add_u32_e32 v145, s18, v141
	ds_read_b128 v[162:165], v145
	ds_read_b128 v[166:169], v145 offset:1024
	ds_read_b128 v[170:173], v145 offset:2048
	ds_read_b128 v[174:177], v145 offset:3072
	v_lshl_add_u64 v[194:195], s[60:61], 0, v[136:137]
	s_add_i32 m0, s29, 0xc000
	global_load_lds_dwordx4 v[194:195], off
	v_lshl_add_u64 v[194:195], s[60:61], 0, v[138:139]
	s_add_i32 m0, s29, 0xe000
	s_nop 0
	global_load_lds_dwordx4 v[194:195], off
	s_waitcnt vmcnt(8)
	s_waitcnt lgkmcnt(0)
	s_barrier
	s_setprio 1
	v_mfma_f32_16x16x32_bf16 v[114:117], v[146:149], v[178:181], v[114:117]
	v_mfma_f32_16x16x32_bf16 v[114:117], v[150:153], v[182:185], v[114:117]
	v_mfma_f32_16x16x32_bf16 v[98:101], v[146:149], v[186:189], v[98:101]
	v_mfma_f32_16x16x32_bf16 v[98:101], v[150:153], v[190:193], v[98:101]
	v_mfma_f32_16x16x32_bf16 v[82:85], v[146:149], v[202:205], v[82:85]
	v_mfma_f32_16x16x32_bf16 v[82:85], v[150:153], v[206:209], v[82:85]
	v_mfma_f32_16x16x32_bf16 v[66:69], v[146:149], v[210:213], v[66:69]
	v_mfma_f32_16x16x32_bf16 v[66:69], v[150:153], v[214:217], v[66:69]
	v_mfma_f32_16x16x32_bf16 v[118:121], v[154:157], v[178:181], v[118:121]
	v_mfma_f32_16x16x32_bf16 v[118:121], v[158:161], v[182:185], v[118:121]
	v_mfma_f32_16x16x32_bf16 v[102:105], v[154:157], v[186:189], v[102:105]
	v_mfma_f32_16x16x32_bf16 v[102:105], v[158:161], v[190:193], v[102:105]
	v_mfma_f32_16x16x32_bf16 v[86:89], v[154:157], v[202:205], v[86:89]
	v_mfma_f32_16x16x32_bf16 v[86:89], v[158:161], v[206:209], v[86:89]
	v_mfma_f32_16x16x32_bf16 v[70:73], v[154:157], v[210:213], v[70:73]
	v_mfma_f32_16x16x32_bf16 v[70:73], v[158:161], v[214:217], v[70:73]
	v_mfma_f32_16x16x32_bf16 v[122:125], v[162:165], v[178:181], v[122:125]
	v_mfma_f32_16x16x32_bf16 v[122:125], v[166:169], v[182:185], v[122:125]
	v_mfma_f32_16x16x32_bf16 v[106:109], v[162:165], v[186:189], v[106:109]
	v_mfma_f32_16x16x32_bf16 v[106:109], v[166:169], v[190:193], v[106:109]
	v_mfma_f32_16x16x32_bf16 v[90:93], v[162:165], v[202:205], v[90:93]
	v_mfma_f32_16x16x32_bf16 v[90:93], v[166:169], v[206:209], v[90:93]
	v_mfma_f32_16x16x32_bf16 v[74:77], v[162:165], v[210:213], v[74:77]
	v_mfma_f32_16x16x32_bf16 v[74:77], v[166:169], v[214:217], v[74:77]
	v_mfma_f32_16x16x32_bf16 v[126:129], v[170:173], v[178:181], v[126:129]
	v_mfma_f32_16x16x32_bf16 v[126:129], v[174:177], v[182:185], v[126:129]
	v_mfma_f32_16x16x32_bf16 v[110:113], v[170:173], v[186:189], v[110:113]
	v_mfma_f32_16x16x32_bf16 v[110:113], v[174:177], v[190:193], v[110:113]
	v_mfma_f32_16x16x32_bf16 v[94:97], v[170:173], v[202:205], v[94:97]
	v_mfma_f32_16x16x32_bf16 v[94:97], v[174:177], v[206:209], v[94:97]
	v_mfma_f32_16x16x32_bf16 v[78:81], v[170:173], v[210:213], v[78:81]
	v_mfma_f32_16x16x32_bf16 v[78:81], v[174:177], v[214:217], v[78:81]
	s_setprio 0
	s_barrier
	s_add_i32 s38, s39, s27
	v_lshl_add_u64 v[194:195], s[56:57], 0, v[0:1]
	s_mov_b32 m0, s38
	ds_read_b128 v[178:181], v144 offset:16384
	ds_read_b128 v[182:185], v144 offset:17408
	ds_read_b128 v[186:189], v144 offset:18432
	ds_read_b128 v[190:193], v144 offset:19456
	ds_read_b128 v[202:205], v144 offset:20480
	ds_read_b128 v[206:209], v144 offset:21504
	ds_read_b128 v[210:213], v144 offset:22528
	ds_read_b128 v[214:217], v144 offset:23552
	global_load_lds_dwordx4 v[194:195], off
	s_add_i32 m0, s38, 0x2000
	s_add_u32 s38, s56, 0x40000
	v_lshl_add_u64 v[218:219], s[56:57], 0, v[130:131]
	s_addc_u32 s39, s57, 0
	s_add_i32 s18, s18, s27
	global_load_lds_dwordx4 v[218:219], off
	v_lshl_add_u64 v[220:221], s[38:39], 0, v[0:1]
	s_mov_b32 m0, s18
	v_lshl_add_u64 v[222:223], s[64:65], 0, v[132:133]
	global_load_lds_dwordx4 v[220:221], off
	v_lshl_add_u64 v[220:221], s[38:39], 0, v[130:131]
	s_add_i32 m0, s18, 0x2000
	s_nop 0
	global_load_lds_dwordx4 v[220:221], off
	v_lshl_add_u64 v[220:221], s[64:65], 0, v[134:135]
	s_mov_b32 m0, s29
	s_nop 0
	global_load_lds_dwordx4 v[220:221], off
	s_mov_b32 m0, s33
	s_nop 0
	global_load_lds_dwordx4 v[222:223], off
	s_waitcnt vmcnt(8)
	s_waitcnt lgkmcnt(0)
	s_barrier
; #define PG8_STAGE(bufoff, gbase, voff) do { _Pragma("unroll") for (int _i = 0; _i < 2; ++_i) \
;         __builtin_amdgcn_global_load_lds((const unsigned*)((const char*)(gbase) + (voff)[_i]), (PG8_LAS unsigned*)(lds + (bufoff) + ldsw + _i * 8192), 16, 0, 0); } while (0)
; #define PG8_LDA(dst, b, h) do { _Pragma("unroll") for (int m = 0; m < 4; ++m) _Pragma("unroll") for (int k = 0; k < 2; ++k) dst[m][k] = *(const PG8_LAS bf16x8*)(lds + PG8_SA(b, h) + aoff + m * 2048 + k * 1024); } while (0)
; #define PG8_LDB(dst, b, h) do { _Pragma("unroll") for (int n = 0; n < 2; ++n) _Pragma("unroll") for (int k = 0; k < 2; ++k) dst[n][k] = *(const PG8_LAS bf16x8*)(lds + PG8_SB(b, h) + boff + n * 2048 + k * 1024); } while (0)
; #define PG8_MMA(ai, bj, At, Bt) do { __builtin_amdgcn_s_setprio(1); _Pragma("unroll") for (int m = 0; m < 4; ++m) _Pragma("unroll") for (int n = 0; n < 2; ++n) _Pragma("unroll") for (int k = 0; k < 2; ++k) \
;         acc[ai][bj][m][n] = __builtin_amdgcn_mfma_f32_16x16x32_bf16(Bt[n][k], At[m][k], acc[ai][bj][m][n], 0, 0, 0); __builtin_amdgcn_s_setprio(0); } while (0)
; #define PG8_WAIT_V(n) asm volatile("s_waitcnt vmcnt(" #n ")" ::: "memory")
; #define PG8_WAIT_L(n) asm volatile("s_waitcnt lgkmcnt(" #n ")" ::: "memory")
; #define PG8_BAR __builtin_amdgcn_s_barrier()
; #define PG8_SCHED __builtin_amdgcn_sched_barrier(0)
; template <class Epi, class Sched, bool ALIGN_EPI = false, bool SP2 = false>
; __device__ __forceinline__ void gemm_phase(PG8_LAS unsigned char* lds, const Gemm g, const Sched& S, const Epi& E) {
;     ...
;             PG8_WAIT_V(8); PG8_WAIT_L(0); PG8_BAR; PG8_MMA(1, 0, At, B0); PG8_MMA(1, 1, At, B1); PG8_BAR; PG8_SCHED;
;             PG8_LDB(B0, 1, 0); PG8_LDB(B1, 1, 1); PG8_SCHED; PG8_LDA(At, 1, 0); PG8_STAGE(PG8_SA(0, 1), a2 + hstep, voffA);
;             PG8_WAIT_V(8); PG8_WAIT_L(0); PG8_BAR; PG8_MMA(0, 0, At, B0); PG8_MMA(0, 1, At, B1); PG8_BAR; PG8_SCHED;
	s_setprio 1
	v_mfma_f32_16x16x32_bf16 v[50:53], v[146:149], v[178:181], v[50:53]
	v_mfma_f32_16x16x32_bf16 v[50:53], v[150:153], v[182:185], v[50:53]
	v_mfma_f32_16x16x32_bf16 v[34:37], v[146:149], v[186:189], v[34:37]
	v_mfma_f32_16x16x32_bf16 v[34:37], v[150:153], v[190:193], v[34:37]
	v_mfma_f32_16x16x32_bf16 v[18:21], v[146:149], v[202:205], v[18:21]
	v_mfma_f32_16x16x32_bf16 v[18:21], v[150:153], v[206:209], v[18:21]
	v_mfma_f32_16x16x32_bf16 v[2:5], v[146:149], v[210:213], v[2:5]
	v_mfma_f32_16x16x32_bf16 v[2:5], v[150:153], v[214:217], v[2:5]
	v_mfma_f32_16x16x32_bf16 v[54:57], v[154:157], v[178:181], v[54:57]
	v_mfma_f32_16x16x32_bf16 v[54:57], v[158:161], v[182:185], v[54:57]
	v_mfma_f32_16x16x32_bf16 v[38:41], v[154:157], v[186:189], v[38:41]
	v_mfma_f32_16x16x32_bf16 v[38:41], v[158:161], v[190:193], v[38:41]
	v_mfma_f32_16x16x32_bf16 v[22:25], v[154:157], v[202:205], v[22:25]
	v_mfma_f32_16x16x32_bf16 v[22:25], v[158:161], v[206:209], v[22:25]
	v_mfma_f32_16x16x32_bf16 v[6:9], v[154:157], v[210:213], v[6:9]
	v_mfma_f32_16x16x32_bf16 v[6:9], v[158:161], v[214:217], v[6:9]
	v_mfma_f32_16x16x32_bf16 v[58:61], v[162:165], v[178:181], v[58:61]
	v_mfma_f32_16x16x32_bf16 v[58:61], v[166:169], v[182:185], v[58:61]
	v_mfma_f32_16x16x32_bf16 v[42:45], v[162:165], v[186:189], v[42:45]
	v_mfma_f32_16x16x32_bf16 v[42:45], v[166:169], v[190:193], v[42:45]
	v_mfma_f32_16x16x32_bf16 v[26:29], v[162:165], v[202:205], v[26:29]
	v_mfma_f32_16x16x32_bf16 v[26:29], v[166:169], v[206:209], v[26:29]
	v_mfma_f32_16x16x32_bf16 v[10:13], v[162:165], v[210:213], v[10:13]
	v_mfma_f32_16x16x32_bf16 v[10:13], v[166:169], v[214:217], v[10:13]
	v_mfma_f32_16x16x32_bf16 v[62:65], v[170:173], v[178:181], v[62:65]
	v_mfma_f32_16x16x32_bf16 v[62:65], v[174:177], v[182:185], v[62:65]
	v_mfma_f32_16x16x32_bf16 v[46:49], v[170:173], v[186:189], v[46:49]
	v_mfma_f32_16x16x32_bf16 v[46:49], v[174:177], v[190:193], v[46:49]
	v_mfma_f32_16x16x32_bf16 v[30:33], v[170:173], v[202:205], v[30:33]
	v_mfma_f32_16x16x32_bf16 v[30:33], v[174:177], v[206:209], v[30:33]
	v_mfma_f32_16x16x32_bf16 v[14:17], v[170:173], v[210:213], v[14:17]
	v_mfma_f32_16x16x32_bf16 v[14:17], v[174:177], v[214:217], v[14:17]
	s_setprio 0
	s_barrier
	s_add_i32 s18, 0, 0x18000
	v_add_u32_e32 v145, s18, v141
	s_add_i32 s83, 0, 0x1c000
	ds_read_b128 v[178:181], v144 offset:32768
	ds_read_b128 v[182:185], v144 offset:33792
	ds_read_b128 v[186:189], v144 offset:34816
	ds_read_b128 v[190:193], v144 offset:35840
	ds_read_b128 v[202:205], v144 offset:36864
	ds_read_b128 v[206:209], v144 offset:37888
	ds_read_b128 v[210:213], v144 offset:38912
	ds_read_b128 v[214:217], v144 offset:39936
	ds_read_b128 v[146:149], v145
	ds_read_b128 v[150:153], v145 offset:1024
	ds_read_b128 v[154:157], v145 offset:2048
	ds_read_b128 v[158:161], v145 offset:3072
	v_add_u32_e32 v145, s83, v141
	ds_read_b128 v[162:165], v145
	ds_read_b128 v[166:169], v145 offset:1024
	ds_read_b128 v[170:173], v145 offset:2048
	ds_read_b128 v[174:177], v145 offset:3072
	s_add_u32 s38, s64, 0x40000
	s_addc_u32 s39, s65, 0
	s_mov_b32 m0, s58
	v_lshl_add_u64 v[224:225], s[38:39], 0, v[134:135]
	global_load_lds_dwordx4 v[224:225], off
	v_lshl_add_u64 v[224:225], s[38:39], 0, v[132:133]
	s_mov_b32 m0, s69
	s_nop 0
	global_load_lds_dwordx4 v[224:225], off
	s_waitcnt vmcnt(8)
	s_waitcnt lgkmcnt(0)
	s_barrier
	s_setprio 1
	v_mfma_f32_16x16x32_bf16 v[114:117], v[146:149], v[178:181], v[114:117]
	v_mfma_f32_16x16x32_bf16 v[114:117], v[150:153], v[182:185], v[114:117]
	v_mfma_f32_16x16x32_bf16 v[98:101], v[146:149], v[186:189], v[98:101]
	v_mfma_f32_16x16x32_bf16 v[98:101], v[150:153], v[190:193], v[98:101]
	v_mfma_f32_16x16x32_bf16 v[82:85], v[146:149], v[202:205], v[82:85]
	v_mfma_f32_16x16x32_bf16 v[82:85], v[150:153], v[206:209], v[82:85]
	v_mfma_f32_16x16x32_bf16 v[66:69], v[146:149], v[210:213], v[66:69]
	v_mfma_f32_16x16x32_bf16 v[66:69], v[150:153], v[214:217], v[66:69]
	v_mfma_f32_16x16x32_bf16 v[118:121], v[154:157], v[178:181], v[118:121]
	v_mfma_f32_16x16x32_bf16 v[118:121], v[158:161], v[182:185], v[118:121]
	v_mfma_f32_16x16x32_bf16 v[102:105], v[154:157], v[186:189], v[102:105]
	v_mfma_f32_16x16x32_bf16 v[102:105], v[158:161], v[190:193], v[102:105]
	v_mfma_f32_16x16x32_bf16 v[86:89], v[154:157], v[202:205], v[86:89]
	v_mfma_f32_16x16x32_bf16 v[86:89], v[158:161], v[206:209], v[86:89]
	v_mfma_f32_16x16x32_bf16 v[70:73], v[154:157], v[210:213], v[70:73]
	v_mfma_f32_16x16x32_bf16 v[70:73], v[158:161], v[214:217], v[70:73]
	v_mfma_f32_16x16x32_bf16 v[122:125], v[162:165], v[178:181], v[122:125]
	v_mfma_f32_16x16x32_bf16 v[122:125], v[166:169], v[182:185], v[122:125]
	v_mfma_f32_16x16x32_bf16 v[106:109], v[162:165], v[186:189], v[106:109]
	v_mfma_f32_16x16x32_bf16 v[106:109], v[166:169], v[190:193], v[106:109]
	v_mfma_f32_16x16x32_bf16 v[90:93], v[162:165], v[202:205], v[90:93]
	v_mfma_f32_16x16x32_bf16 v[90:93], v[166:169], v[206:209], v[90:93]
	v_mfma_f32_16x16x32_bf16 v[74:77], v[162:165], v[210:213], v[74:77]
	v_mfma_f32_16x16x32_bf16 v[74:77], v[166:169], v[214:217], v[74:77]
	v_mfma_f32_16x16x32_bf16 v[126:129], v[170:173], v[178:181], v[126:129]
	v_mfma_f32_16x16x32_bf16 v[126:129], v[174:177], v[182:185], v[126:129]
	v_mfma_f32_16x16x32_bf16 v[110:113], v[170:173], v[186:189], v[110:113]
	v_mfma_f32_16x16x32_bf16 v[110:113], v[174:177], v[190:193], v[110:113]
	v_mfma_f32_16x16x32_bf16 v[94:97], v[170:173], v[202:205], v[94:97]
	v_mfma_f32_16x16x32_bf16 v[94:97], v[174:177], v[206:209], v[94:97]
	v_mfma_f32_16x16x32_bf16 v[78:81], v[170:173], v[210:213], v[78:81]
	v_mfma_f32_16x16x32_bf16 v[78:81], v[174:177], v[214:217], v[78:81]
	s_setprio 0
	s_barrier
; #define PG8_STAGE(bufoff, gbase, voff) do { _Pragma("unroll") for (int _i = 0; _i < 2; ++_i) \
;         __builtin_amdgcn_global_load_lds((const unsigned*)((const char*)(gbase) + (voff)[_i]), (PG8_LAS unsigned*)(lds + (bufoff) + ldsw + _i * 8192), 16, 0, 0); } while (0)
; #define PG8_LDA(dst, b, h) do { _Pragma("unroll") for (int m = 0; m < 4; ++m) _Pragma("unroll") for (int k = 0; k < 2; ++k) dst[m][k] = *(const PG8_LAS bf16x8*)(lds + PG8_SA(b, h) + aoff + m * 2048 + k * 1024); } while (0)
; #define PG8_MMA(ai, bj, At, Bt) do { __builtin_amdgcn_s_setprio(1); _Pragma("unroll") for (int m = 0; m < 4; ++m) _Pragma("unroll") for (int n = 0; n < 2; ++n) _Pragma("unroll") for (int k = 0; k < 2; ++k) \
;         acc[ai][bj][m][n] = __builtin_amdgcn_mfma_f32_16x16x32_bf16(Bt[n][k], At[m][k], acc[ai][bj][m][n], 0, 0, 0); __builtin_amdgcn_s_setprio(0); } while (0)
; #define PG8_WAIT_V(n) asm volatile("s_waitcnt vmcnt(" #n ")" ::: "memory")
; #define PG8_WAIT_L(n) asm volatile("s_waitcnt lgkmcnt(" #n ")" ::: "memory")
; #define PG8_BAR __builtin_amdgcn_s_barrier()
; #define PG8_SCHED __builtin_amdgcn_sched_barrier(0)
; template <class Epi, class Sched, bool ALIGN_EPI = false, bool SP2 = false>
; __device__ __forceinline__ void gemm_phase(PG8_LAS unsigned char* lds, const Gemm g, const Sched& S, const Epi& E) {
;     ...
;         for (int t = 0; t < nt; t += 2) {
;             const bool last = (t == nt - 2);
;     ...
;             PG8_LDA(At, 1, 1); PG8_STAGE(PG8_SB(1, 0), b3, voffB); PG8_STAGE(PG8_SB(1, 1), b3 + hstep, voffB); PG8_STAGE(PG8_SA(1, 0), a3, voffA);
;             PG8_WAIT_V(8); PG8_WAIT_L(0); PG8_BAR; PG8_MMA(1, 0, At, B0); PG8_MMA(1, 1, At, B1); PG8_BAR; PG8_SCHED;
	s_add_i32 s18, s18, s27
	v_lshl_add_u64 v[194:195], v[194:195], 0, s[30:31]
	s_mov_b32 m0, s18
	ds_read_b128 v[178:181], v144 offset:49152
	ds_read_b128 v[182:185], v144 offset:50176
	ds_read_b128 v[186:189], v144 offset:51200
	ds_read_b128 v[190:193], v144 offset:52224
	ds_read_b128 v[202:205], v144 offset:53248
	ds_read_b128 v[206:209], v144 offset:54272
	ds_read_b128 v[210:213], v144 offset:55296
	ds_read_b128 v[214:217], v144 offset:56320
	global_load_lds_dwordx4 v[194:195], off
	s_add_i32 m0, s18, 0x2000
	s_add_u32 s38, s56, 0x40080
	v_lshl_add_u64 v[194:195], v[218:219], 0, s[30:31]
	s_addc_u32 s39, s57, 0
	s_add_i32 s18, s83, s27
	global_load_lds_dwordx4 v[194:195], off
	v_lshl_add_u64 v[194:195], s[38:39], 0, v[0:1]
	s_mov_b32 m0, s18
	s_nop 0
	global_load_lds_dwordx4 v[194:195], off
	v_lshl_add_u64 v[194:195], s[38:39], 0, v[130:131]
	s_add_i32 m0, s18, 0x2000
	s_nop 0
	global_load_lds_dwordx4 v[194:195], off
	v_lshl_add_u64 v[194:195], v[220:221], 0, s[30:31]
	s_mov_b32 m0, s71
	s_nop 0
	global_load_lds_dwordx4 v[194:195], off
	v_lshl_add_u64 v[194:195], v[222:223], 0, s[30:31]
	s_mov_b32 m0, s72
	s_nop 0
	global_load_lds_dwordx4 v[194:195], off
	s_waitcnt vmcnt(8)
	s_waitcnt lgkmcnt(0)
	s_barrier
	s_setprio 1
	v_mfma_f32_16x16x32_bf16 v[50:53], v[146:149], v[178:181], v[50:53]
	v_mfma_f32_16x16x32_bf16 v[50:53], v[150:153], v[182:185], v[50:53]
	v_mfma_f32_16x16x32_bf16 v[34:37], v[146:149], v[186:189], v[34:37]
	v_mfma_f32_16x16x32_bf16 v[34:37], v[150:153], v[190:193], v[34:37]
	v_mfma_f32_16x16x32_bf16 v[18:21], v[146:149], v[202:205], v[18:21]
	v_mfma_f32_16x16x32_bf16 v[18:21], v[150:153], v[206:209], v[18:21]
	v_mfma_f32_16x16x32_bf16 v[2:5], v[146:149], v[210:213], v[2:5]
	v_mfma_f32_16x16x32_bf16 v[2:5], v[150:153], v[214:217], v[2:5]
	v_mfma_f32_16x16x32_bf16 v[54:57], v[154:157], v[178:181], v[54:57]
	v_mfma_f32_16x16x32_bf16 v[54:57], v[158:161], v[182:185], v[54:57]
	v_mfma_f32_16x16x32_bf16 v[38:41], v[154:157], v[186:189], v[38:41]
	v_mfma_f32_16x16x32_bf16 v[38:41], v[158:161], v[190:193], v[38:41]
	v_mfma_f32_16x16x32_bf16 v[22:25], v[154:157], v[202:205], v[22:25]
	v_mfma_f32_16x16x32_bf16 v[22:25], v[158:161], v[206:209], v[22:25]
	v_mfma_f32_16x16x32_bf16 v[6:9], v[154:157], v[210:213], v[6:9]
	v_mfma_f32_16x16x32_bf16 v[6:9], v[158:161], v[214:217], v[6:9]
	v_mfma_f32_16x16x32_bf16 v[58:61], v[162:165], v[178:181], v[58:61]
	v_mfma_f32_16x16x32_bf16 v[58:61], v[166:169], v[182:185], v[58:61]
	v_mfma_f32_16x16x32_bf16 v[42:45], v[162:165], v[186:189], v[42:45]
	v_mfma_f32_16x16x32_bf16 v[42:45], v[166:169], v[190:193], v[42:45]
	v_mfma_f32_16x16x32_bf16 v[26:29], v[162:165], v[202:205], v[26:29]
	v_mfma_f32_16x16x32_bf16 v[26:29], v[166:169], v[206:209], v[26:29]
	v_mfma_f32_16x16x32_bf16 v[10:13], v[162:165], v[210:213], v[10:13]
	v_mfma_f32_16x16x32_bf16 v[10:13], v[166:169], v[214:217], v[10:13]
	v_mfma_f32_16x16x32_bf16 v[62:65], v[170:173], v[178:181], v[62:65]
	v_mfma_f32_16x16x32_bf16 v[62:65], v[174:177], v[182:185], v[62:65]
	v_mfma_f32_16x16x32_bf16 v[46:49], v[170:173], v[186:189], v[46:49]
	v_mfma_f32_16x16x32_bf16 v[46:49], v[174:177], v[190:193], v[46:49]
	v_mfma_f32_16x16x32_bf16 v[30:33], v[170:173], v[202:205], v[30:33]
	v_mfma_f32_16x16x32_bf16 v[30:33], v[174:177], v[206:209], v[30:33]
	v_mfma_f32_16x16x32_bf16 v[14:17], v[170:173], v[210:213], v[14:17]
	v_mfma_f32_16x16x32_bf16 v[14:17], v[174:177], v[214:217], v[14:17]
	s_setprio 0
	s_barrier
	s_add_i32 s82, s82, 2
	s_add_u32 s60, s60, 0x100
	s_addc_u32 s61, s61, 0
	s_add_u32 s80, s80, 0x100
	s_addc_u32 s81, s81, 0
	s_cmp_gt_u32 s82, 13
	s_cbranch_scc0 .LBB0_220
	s_and_b64 vcc, exec, s[44:45]
	s_cbranch_vccz .LBB0_223
	s_barrier

; #define PG8_STAGE(bufoff, gbase, voff) do { _Pragma("unroll") for (int _i = 0; _i < 2; ++_i) \
;         __builtin_amdgcn_global_load_lds((const unsigned*)((const char*)(gbase) + (voff)[_i]), (PG8_LAS unsigned*)(lds + (bufoff) + ldsw + _i * 8192), 16, 0, 0); } while (0)
; #define PG8_LDA(dst, b, h) do { _Pragma("unroll") for (int m = 0; m < 4; ++m) _Pragma("unroll") for (int k = 0; k < 2; ++k) dst[m][k] = *(const PG8_LAS bf16x8*)(lds + PG8_SA(b, h) + aoff + m * 2048 + k * 1024); } while (0)
; #define PG8_LDB(dst, b, h) do { _Pragma("unroll") for (int n = 0; n < 2; ++n) _Pragma("unroll") for (int k = 0; k < 2; ++k) dst[n][k] = *(const PG8_LAS bf16x8*)(lds + PG8_SB(b, h) + boff + n * 2048 + k * 1024); } while (0)
; #define PG8_MMA(ai, bj, At, Bt) do { __builtin_amdgcn_s_setprio(1); _Pragma("unroll") for (int m = 0; m < 4; ++m) _Pragma("unroll") for (int n = 0; n < 2; ++n) _Pragma("unroll") for (int k = 0; k < 2; ++k) \
;         acc[ai][bj][m][n] = __builtin_amdgcn_mfma_f32_16x16x32_bf16(Bt[n][k], At[m][k], acc[ai][bj][m][n], 0, 0, 0); __builtin_amdgcn_s_setprio(0); } while (0)
; #define PG8_WAIT_V(n) asm volatile("s_waitcnt vmcnt(" #n ")" ::: "memory")
; #define PG8_WAIT_L(n) asm volatile("s_waitcnt lgkmcnt(" #n ")" ::: "memory")
; #define PG8_BAR __builtin_amdgcn_s_barrier()
; #define PG8_SCHED __builtin_amdgcn_sched_barrier(0)
; template <class Epi, class Sched, bool ALIGN_EPI = false, bool SP2 = false>
; __device__ __forceinline__ void gemm_phase(PG8_LAS unsigned char* lds, const Gemm g, const Sched& S, const Epi& E) {
;     ...
;             PG8_LDB(B0, 0, 0); PG8_LDB(B1, 0, 1); PG8_SCHED; PG8_LDA(At, 0, 0); PG8_STAGE(PG8_SA(1, 1), a1 + hstep, voffA);
;             PG8_WAIT_V(8); PG8_WAIT_L(0); PG8_BAR; PG8_MMA(0, 0, At, B0); PG8_MMA(0, 1, At, B1); PG8_BAR; PG8_SCHED;
;             PG8_LDA(At, 0, 1); PG8_STAGE(PG8_SB(0, 0), b2, voffB); PG8_STAGE(PG8_SB(0, 1), b2 + hstep, voffB); PG8_STAGE(PG8_SA(0, 0), a2, voffA);
;             PG8_WAIT_V(8); PG8_WAIT_L(0); PG8_BAR; PG8_MMA(1, 0, At, B0); PG8_MMA(1, 1, At, B1); PG8_BAR; PG8_SCHED;
.LBB0_274:
	s_add_i32 vcc_lo, s46, 2
	s_add_u32 s38, s48, 0x80
	s_addc_u32 s39, s49, 0
	s_add_i32 vcc_hi, 0, 0x10000
	s_cmp_eq_u32 s99, s46
	s_cselect_b32 s47, s81, s39
	s_cselect_b32 s46, s80, s38
	s_cselect_b32 s39, s83, s51
	s_cselect_b32 s38, s82, s50
	s_add_i32 s18, 0, 0x14000
	v_add_u32_e32 v142, vcc_hi, v245
	v_add_u32_e32 v158, s18, v245
	ds_read_b128 v[162:165], v247
	ds_read_b128 v[166:169], v247 offset:1024
	ds_read_b128 v[170:173], v247 offset:2048
	ds_read_b128 v[174:177], v247 offset:3072
	ds_read_b128 v[178:181], v247 offset:4096
	ds_read_b128 v[182:185], v247 offset:5120
	ds_read_b128 v[186:189], v247 offset:6144
	ds_read_b128 v[190:193], v247 offset:7168
	ds_read_b128 v[110:113], v142
	ds_read_b128 v[118:121], v142 offset:1024
	ds_read_b128 v[138:141], v142 offset:2048
	ds_read_b128 v[142:145], v142 offset:3072
	ds_read_b128 v[146:149], v158
	ds_read_b128 v[150:153], v158 offset:1024
	ds_read_b128 v[154:157], v158 offset:2048
	ds_read_b128 v[158:161], v158 offset:3072
	v_lshl_add_u64 v[210:211], s[48:49], 0, v[206:207]
	s_add_i32 m0, s92, 0xc000
	global_load_lds_dwordx4 v[210:211], off
	v_lshl_add_u64 v[210:211], s[48:49], 0, v[208:209]
	s_add_i32 m0, s92, 0xe000
	s_nop 0
	global_load_lds_dwordx4 v[210:211], off
	s_waitcnt vmcnt(8)
	s_waitcnt lgkmcnt(0)
	s_barrier
	s_setprio 1
	v_mfma_f32_16x16x32_bf16 v[130:133], v[110:113], v[162:165], v[130:133]
	v_mfma_f32_16x16x32_bf16 v[130:133], v[118:121], v[166:169], v[130:133]
	v_mfma_f32_16x16x32_bf16 v[114:117], v[110:113], v[170:173], v[114:117]
	v_mfma_f32_16x16x32_bf16 v[114:117], v[118:121], v[174:177], v[114:117]
	v_mfma_f32_16x16x32_bf16 v[94:97], v[110:113], v[178:181], v[94:97]
	v_mfma_f32_16x16x32_bf16 v[94:97], v[118:121], v[182:185], v[94:97]
	v_mfma_f32_16x16x32_bf16 v[78:81], v[110:113], v[186:189], v[78:81]
	v_mfma_f32_16x16x32_bf16 v[78:81], v[118:121], v[190:193], v[78:81]
	v_mfma_f32_16x16x32_bf16 v[134:137], v[138:141], v[162:165], v[134:137]
	v_mfma_f32_16x16x32_bf16 v[134:137], v[142:145], v[166:169], v[134:137]
	v_mfma_f32_16x16x32_bf16 v[106:109], v[138:141], v[170:173], v[106:109]
	v_mfma_f32_16x16x32_bf16 v[106:109], v[142:145], v[174:177], v[106:109]
	v_mfma_f32_16x16x32_bf16 v[90:93], v[138:141], v[178:181], v[90:93]
	v_mfma_f32_16x16x32_bf16 v[90:93], v[142:145], v[182:185], v[90:93]
	v_mfma_f32_16x16x32_bf16 v[74:77], v[138:141], v[186:189], v[74:77]
	v_mfma_f32_16x16x32_bf16 v[74:77], v[142:145], v[190:193], v[74:77]
	v_mfma_f32_16x16x32_bf16 v[126:129], v[146:149], v[162:165], v[126:129]
	v_mfma_f32_16x16x32_bf16 v[126:129], v[150:153], v[166:169], v[126:129]
	v_mfma_f32_16x16x32_bf16 v[102:105], v[146:149], v[170:173], v[102:105]
	v_mfma_f32_16x16x32_bf16 v[102:105], v[150:153], v[174:177], v[102:105]
	v_mfma_f32_16x16x32_bf16 v[86:89], v[146:149], v[178:181], v[86:89]
	v_mfma_f32_16x16x32_bf16 v[86:89], v[150:153], v[182:185], v[86:89]
	v_mfma_f32_16x16x32_bf16 v[70:73], v[146:149], v[186:189], v[70:73]
	v_mfma_f32_16x16x32_bf16 v[70:73], v[150:153], v[190:193], v[70:73]
	v_mfma_f32_16x16x32_bf16 v[122:125], v[154:157], v[162:165], v[122:125]
	v_mfma_f32_16x16x32_bf16 v[122:125], v[158:161], v[166:169], v[122:125]
	v_mfma_f32_16x16x32_bf16 v[98:101], v[154:157], v[170:173], v[98:101]
	v_mfma_f32_16x16x32_bf16 v[98:101], v[158:161], v[174:177], v[98:101]
	v_mfma_f32_16x16x32_bf16 v[82:85], v[154:157], v[178:181], v[82:85]
	v_mfma_f32_16x16x32_bf16 v[82:85], v[158:161], v[182:185], v[82:85]
	v_mfma_f32_16x16x32_bf16 v[66:69], v[154:157], v[186:189], v[66:69]
	v_mfma_f32_16x16x32_bf16 v[66:69], v[158:161], v[190:193], v[66:69]
	s_setprio 0
	s_barrier
	s_add_i32 vcc_hi, vcc_hi, s6
	v_lshl_add_u64 v[210:211], s[38:39], 0, v[0:1]
	s_mov_b32 m0, vcc_hi
	ds_read_b128 v[162:165], v247 offset:16384
	ds_read_b128 v[166:169], v247 offset:17408
	ds_read_b128 v[170:173], v247 offset:18432
	ds_read_b128 v[174:177], v247 offset:19456
	ds_read_b128 v[178:181], v247 offset:20480
	ds_read_b128 v[182:185], v247 offset:21504
	ds_read_b128 v[186:189], v247 offset:22528
	ds_read_b128 v[190:193], v247 offset:23552
	global_load_lds_dwordx4 v[210:211], off
	s_add_i32 m0, vcc_hi, 0x2000
	v_lshl_add_u64 v[212:213], s[38:39], 0, v[204:205]
	s_add_u32 s38, s38, s58
	s_addc_u32 s39, s39, 0
	s_add_i32 s18, s18, s6
	global_load_lds_dwordx4 v[212:213], off
	v_lshl_add_u64 v[214:215], s[38:39], 0, v[0:1]
	s_mov_b32 m0, s18
	v_lshl_add_u64 v[216:217], s[38:39], 0, v[204:205]
	global_load_lds_dwordx4 v[214:215], off
	s_add_i32 m0, s18, 0x2000
	v_lshl_add_u64 v[218:219], s[46:47], 0, v[194:195]
	global_load_lds_dwordx4 v[216:217], off
	s_mov_b32 m0, s92
	v_lshl_add_u64 v[220:221], s[46:47], 0, v[202:203]
	global_load_lds_dwordx4 v[218:219], off
	s_mov_b32 m0, s93
	s_nop 0
	global_load_lds_dwordx4 v[220:221], off
	s_waitcnt vmcnt(8)
	s_waitcnt lgkmcnt(0)
	s_barrier
; #define PG8_STAGE(bufoff, gbase, voff) do { _Pragma("unroll") for (int _i = 0; _i < 2; ++_i) \
;         __builtin_amdgcn_global_load_lds((const unsigned*)((const char*)(gbase) + (voff)[_i]), (PG8_LAS unsigned*)(lds + (bufoff) + ldsw + _i * 8192), 16, 0, 0); } while (0)
; #define PG8_LDA(dst, b, h) do { _Pragma("unroll") for (int m = 0; m < 4; ++m) _Pragma("unroll") for (int k = 0; k < 2; ++k) dst[m][k] = *(const PG8_LAS bf16x8*)(lds + PG8_SA(b, h) + aoff + m * 2048 + k * 1024); } while (0)
; #define PG8_LDB(dst, b, h) do { _Pragma("unroll") for (int n = 0; n < 2; ++n) _Pragma("unroll") for (int k = 0; k < 2; ++k) dst[n][k] = *(const PG8_LAS bf16x8*)(lds + PG8_SB(b, h) + boff + n * 2048 + k * 1024); } while (0)
; #define PG8_MMA(ai, bj, At, Bt) do { __builtin_amdgcn_s_setprio(1); _Pragma("unroll") for (int m = 0; m < 4; ++m) _Pragma("unroll") for (int n = 0; n < 2; ++n) _Pragma("unroll") for (int k = 0; k < 2; ++k) \
;         acc[ai][bj][m][n] = __builtin_amdgcn_mfma_f32_16x16x32_bf16(Bt[n][k], At[m][k], acc[ai][bj][m][n], 0, 0, 0); __builtin_amdgcn_s_setprio(0); } while (0)
; #define PG8_WAIT_V(n) asm volatile("s_waitcnt vmcnt(" #n ")" ::: "memory")
; #define PG8_WAIT_L(n) asm volatile("s_waitcnt lgkmcnt(" #n ")" ::: "memory")
; #define PG8_BAR __builtin_amdgcn_s_barrier()
; #define PG8_SCHED __builtin_amdgcn_sched_barrier(0)
; template <class Epi, class Sched, bool ALIGN_EPI = false, bool SP2 = false>
; __device__ __forceinline__ void gemm_phase(PG8_LAS unsigned char* lds, const Gemm g, const Sched& S, const Epi& E) {
;     ...
;             PG8_WAIT_V(8); PG8_WAIT_L(0); PG8_BAR; PG8_MMA(1, 0, At, B0); PG8_MMA(1, 1, At, B1); PG8_BAR; PG8_SCHED;
;             PG8_LDB(B0, 1, 0); PG8_LDB(B1, 1, 1); PG8_SCHED; PG8_LDA(At, 1, 0); PG8_STAGE(PG8_SA(0, 1), a2 + hstep, voffA);
;             PG8_WAIT_V(8); PG8_WAIT_L(0); PG8_BAR; PG8_MMA(0, 0, At, B0); PG8_MMA(0, 1, At, B1); PG8_BAR; PG8_SCHED;
	s_setprio 1
	v_mfma_f32_16x16x32_bf16 v[62:65], v[110:113], v[162:165], v[62:65]
	v_mfma_f32_16x16x32_bf16 v[62:65], v[118:121], v[166:169], v[62:65]
	v_mfma_f32_16x16x32_bf16 v[46:49], v[110:113], v[170:173], v[46:49]
	v_mfma_f32_16x16x32_bf16 v[46:49], v[118:121], v[174:177], v[46:49]
	v_mfma_f32_16x16x32_bf16 v[30:33], v[110:113], v[178:181], v[30:33]
	v_mfma_f32_16x16x32_bf16 v[30:33], v[118:121], v[182:185], v[30:33]
	v_mfma_f32_16x16x32_bf16 v[14:17], v[110:113], v[186:189], v[14:17]
	v_mfma_f32_16x16x32_bf16 v[14:17], v[118:121], v[190:193], v[14:17]
	v_mfma_f32_16x16x32_bf16 v[58:61], v[138:141], v[162:165], v[58:61]
	v_mfma_f32_16x16x32_bf16 v[58:61], v[142:145], v[166:169], v[58:61]
	v_mfma_f32_16x16x32_bf16 v[42:45], v[138:141], v[170:173], v[42:45]
	v_mfma_f32_16x16x32_bf16 v[42:45], v[142:145], v[174:177], v[42:45]
	v_mfma_f32_16x16x32_bf16 v[26:29], v[138:141], v[178:181], v[26:29]
	v_mfma_f32_16x16x32_bf16 v[26:29], v[142:145], v[182:185], v[26:29]
	v_mfma_f32_16x16x32_bf16 v[10:13], v[138:141], v[186:189], v[10:13]
	v_mfma_f32_16x16x32_bf16 v[10:13], v[142:145], v[190:193], v[10:13]
	v_mfma_f32_16x16x32_bf16 v[54:57], v[146:149], v[162:165], v[54:57]
	v_mfma_f32_16x16x32_bf16 v[54:57], v[150:153], v[166:169], v[54:57]
	v_mfma_f32_16x16x32_bf16 v[38:41], v[146:149], v[170:173], v[38:41]
	v_mfma_f32_16x16x32_bf16 v[38:41], v[150:153], v[174:177], v[38:41]
	v_mfma_f32_16x16x32_bf16 v[22:25], v[146:149], v[178:181], v[22:25]
	v_mfma_f32_16x16x32_bf16 v[22:25], v[150:153], v[182:185], v[22:25]
	v_mfma_f32_16x16x32_bf16 v[6:9], v[146:149], v[186:189], v[6:9]
	v_mfma_f32_16x16x32_bf16 v[6:9], v[150:153], v[190:193], v[6:9]
	v_mfma_f32_16x16x32_bf16 v[50:53], v[154:157], v[162:165], v[50:53]
	v_mfma_f32_16x16x32_bf16 v[50:53], v[158:161], v[166:169], v[50:53]
	v_mfma_f32_16x16x32_bf16 v[34:37], v[154:157], v[170:173], v[34:37]
	v_mfma_f32_16x16x32_bf16 v[34:37], v[158:161], v[174:177], v[34:37]
	v_mfma_f32_16x16x32_bf16 v[18:21], v[154:157], v[178:181], v[18:21]
	v_mfma_f32_16x16x32_bf16 v[18:21], v[158:161], v[182:185], v[18:21]
	v_mfma_f32_16x16x32_bf16 v[2:5], v[154:157], v[186:189], v[2:5]
	v_mfma_f32_16x16x32_bf16 v[2:5], v[158:161], v[190:193], v[2:5]
	s_setprio 0
	s_barrier
	s_add_i32 s18, 0, 0x18000
	s_add_i32 vcc_hi, 0, 0x1c000
	v_add_u32_e32 v142, s18, v245
	v_add_u32_e32 v158, vcc_hi, v245
	ds_read_b128 v[162:165], v247 offset:32768
	ds_read_b128 v[166:169], v247 offset:33792
	ds_read_b128 v[170:173], v247 offset:34816
	ds_read_b128 v[174:177], v247 offset:35840
	ds_read_b128 v[178:181], v247 offset:36864
	ds_read_b128 v[182:185], v247 offset:37888
	ds_read_b128 v[186:189], v247 offset:38912
	ds_read_b128 v[190:193], v247 offset:39936
	ds_read_b128 v[110:113], v142
	ds_read_b128 v[118:121], v142 offset:1024
	ds_read_b128 v[138:141], v142 offset:2048
	ds_read_b128 v[142:145], v142 offset:3072
	ds_read_b128 v[146:149], v158
	ds_read_b128 v[150:153], v158 offset:1024
	ds_read_b128 v[154:157], v158 offset:2048
	ds_read_b128 v[158:161], v158 offset:3072
	s_add_u32 s38, s46, s58
	s_addc_u32 s39, s47, 0
	s_mov_b32 m0, s94
	v_lshl_add_u64 v[222:223], s[38:39], 0, v[194:195]
	global_load_lds_dwordx4 v[222:223], off
	v_lshl_add_u64 v[222:223], s[38:39], 0, v[202:203]
	s_mov_b32 m0, s95
	s_nop 0
	global_load_lds_dwordx4 v[222:223], off
	s_waitcnt vmcnt(8)
	s_waitcnt lgkmcnt(0)
	s_barrier
	s_setprio 1
	v_mfma_f32_16x16x32_bf16 v[130:133], v[110:113], v[162:165], v[130:133]
	v_mfma_f32_16x16x32_bf16 v[130:133], v[118:121], v[166:169], v[130:133]
	v_mfma_f32_16x16x32_bf16 v[114:117], v[110:113], v[170:173], v[114:117]
	v_mfma_f32_16x16x32_bf16 v[114:117], v[118:121], v[174:177], v[114:117]
	v_mfma_f32_16x16x32_bf16 v[94:97], v[110:113], v[178:181], v[94:97]
	v_mfma_f32_16x16x32_bf16 v[94:97], v[118:121], v[182:185], v[94:97]
	v_mfma_f32_16x16x32_bf16 v[78:81], v[110:113], v[186:189], v[78:81]
	v_mfma_f32_16x16x32_bf16 v[78:81], v[118:121], v[190:193], v[78:81]
	v_mfma_f32_16x16x32_bf16 v[134:137], v[138:141], v[162:165], v[134:137]
	v_mfma_f32_16x16x32_bf16 v[134:137], v[142:145], v[166:169], v[134:137]
	v_mfma_f32_16x16x32_bf16 v[106:109], v[138:141], v[170:173], v[106:109]
	v_mfma_f32_16x16x32_bf16 v[106:109], v[142:145], v[174:177], v[106:109]
	v_mfma_f32_16x16x32_bf16 v[90:93], v[138:141], v[178:181], v[90:93]
	v_mfma_f32_16x16x32_bf16 v[90:93], v[142:145], v[182:185], v[90:93]
	v_mfma_f32_16x16x32_bf16 v[74:77], v[138:141], v[186:189], v[74:77]
	v_mfma_f32_16x16x32_bf16 v[74:77], v[142:145], v[190:193], v[74:77]
	v_mfma_f32_16x16x32_bf16 v[126:129], v[146:149], v[162:165], v[126:129]
	v_mfma_f32_16x16x32_bf16 v[126:129], v[150:153], v[166:169], v[126:129]
	v_mfma_f32_16x16x32_bf16 v[102:105], v[146:149], v[170:173], v[102:105]
	v_mfma_f32_16x16x32_bf16 v[102:105], v[150:153], v[174:177], v[102:105]
	v_mfma_f32_16x16x32_bf16 v[86:89], v[146:149], v[178:181], v[86:89]
	v_mfma_f32_16x16x32_bf16 v[86:89], v[150:153], v[182:185], v[86:89]
	v_mfma_f32_16x16x32_bf16 v[70:73], v[146:149], v[186:189], v[70:73]
	v_mfma_f32_16x16x32_bf16 v[70:73], v[150:153], v[190:193], v[70:73]
	v_mfma_f32_16x16x32_bf16 v[122:125], v[154:157], v[162:165], v[122:125]
	v_mfma_f32_16x16x32_bf16 v[122:125], v[158:161], v[166:169], v[122:125]
	v_mfma_f32_16x16x32_bf16 v[98:101], v[154:157], v[170:173], v[98:101]
	v_mfma_f32_16x16x32_bf16 v[98:101], v[158:161], v[174:177], v[98:101]
	v_mfma_f32_16x16x32_bf16 v[82:85], v[154:157], v[178:181], v[82:85]
	v_mfma_f32_16x16x32_bf16 v[82:85], v[158:161], v[182:185], v[82:85]
	v_mfma_f32_16x16x32_bf16 v[66:69], v[154:157], v[186:189], v[66:69]
	v_mfma_f32_16x16x32_bf16 v[66:69], v[158:161], v[190:193], v[66:69]
	s_setprio 0
	s_barrier
; #define PG8_STAGE(bufoff, gbase, voff) do { _Pragma("unroll") for (int _i = 0; _i < 2; ++_i) \
;         __builtin_amdgcn_global_load_lds((const unsigned*)((const char*)(gbase) + (voff)[_i]), (PG8_LAS unsigned*)(lds + (bufoff) + ldsw + _i * 8192), 16, 0, 0); } while (0)
; #define PG8_LDA(dst, b, h) do { _Pragma("unroll") for (int m = 0; m < 4; ++m) _Pragma("unroll") for (int k = 0; k < 2; ++k) dst[m][k] = *(const PG8_LAS bf16x8*)(lds + PG8_SA(b, h) + aoff + m * 2048 + k * 1024); } while (0)
; #define PG8_MMA(ai, bj, At, Bt) do { __builtin_amdgcn_s_setprio(1); _Pragma("unroll") for (int m = 0; m < 4; ++m) _Pragma("unroll") for (int n = 0; n < 2; ++n) _Pragma("unroll") for (int k = 0; k < 2; ++k) \
;         acc[ai][bj][m][n] = __builtin_amdgcn_mfma_f32_16x16x32_bf16(Bt[n][k], At[m][k], acc[ai][bj][m][n], 0, 0, 0); __builtin_amdgcn_s_setprio(0); } while (0)
; #define PG8_WAIT_V(n) asm volatile("s_waitcnt vmcnt(" #n ")" ::: "memory")
; #define PG8_WAIT_L(n) asm volatile("s_waitcnt lgkmcnt(" #n ")" ::: "memory")
; #define PG8_BAR __builtin_amdgcn_s_barrier()
; #define PG8_SCHED __builtin_amdgcn_sched_barrier(0)
; template <class Epi, class Sched, bool ALIGN_EPI = false, bool SP2 = false>
; __device__ __forceinline__ void gemm_phase(PG8_LAS unsigned char* lds, const Gemm g, const Sched& S, const Epi& E) {
;     ...
;         for (int t = 0; t < nt; t += 2) {
;             const bool last = (t == nt - 2);
;     ...
;             PG8_LDA(At, 1, 1); PG8_STAGE(PG8_SB(1, 0), b3, voffB); PG8_STAGE(PG8_SB(1, 1), b3 + hstep, voffB); PG8_STAGE(PG8_SA(1, 0), a3, voffA);
;             PG8_WAIT_V(8); PG8_WAIT_L(0); PG8_BAR; PG8_MMA(1, 0, At, B0); PG8_MMA(1, 1, At, B1); PG8_BAR; PG8_SCHED;
	s_add_i32 s18, s18, s6
	v_lshl_add_u64 v[210:211], v[210:211], 0, s[30:31]
	s_mov_b32 m0, s18
	ds_read_b128 v[162:165], v247 offset:49152
	ds_read_b128 v[166:169], v247 offset:50176
	ds_read_b128 v[170:173], v247 offset:51200
	ds_read_b128 v[174:177], v247 offset:52224
	ds_read_b128 v[178:181], v247 offset:53248
	ds_read_b128 v[182:185], v247 offset:54272
	ds_read_b128 v[186:189], v247 offset:55296
	ds_read_b128 v[190:193], v247 offset:56320
	global_load_lds_dwordx4 v[210:211], off
	v_lshl_add_u64 v[210:211], v[212:213], 0, s[30:31]
	s_add_i32 m0, s18, 0x2000
	s_add_i32 s18, vcc_hi, s6
	global_load_lds_dwordx4 v[210:211], off
	v_lshl_add_u64 v[210:211], v[214:215], 0, s[30:31]
	s_mov_b32 m0, s18
	s_nop 0
	global_load_lds_dwordx4 v[210:211], off
	v_lshl_add_u64 v[210:211], v[216:217], 0, s[30:31]
	s_add_i32 m0, s18, 0x2000
	s_nop 0
	global_load_lds_dwordx4 v[210:211], off
	v_lshl_add_u64 v[210:211], v[218:219], 0, s[30:31]
	s_mov_b32 m0, s97
	s_nop 0
	global_load_lds_dwordx4 v[210:211], off
	v_lshl_add_u64 v[210:211], v[220:221], 0, s[30:31]
	s_mov_b32 m0, s98
	s_nop 0
	global_load_lds_dwordx4 v[210:211], off
	s_waitcnt vmcnt(8)
	s_waitcnt lgkmcnt(0)
	s_barrier
	s_setprio 1
	v_mfma_f32_16x16x32_bf16 v[62:65], v[110:113], v[162:165], v[62:65]
	v_mfma_f32_16x16x32_bf16 v[62:65], v[118:121], v[166:169], v[62:65]
	v_mfma_f32_16x16x32_bf16 v[46:49], v[110:113], v[170:173], v[46:49]
	v_mfma_f32_16x16x32_bf16 v[46:49], v[118:121], v[174:177], v[46:49]
	v_mfma_f32_16x16x32_bf16 v[30:33], v[110:113], v[178:181], v[30:33]
	v_mfma_f32_16x16x32_bf16 v[30:33], v[118:121], v[182:185], v[30:33]
	v_mfma_f32_16x16x32_bf16 v[14:17], v[110:113], v[186:189], v[14:17]
	v_mfma_f32_16x16x32_bf16 v[14:17], v[118:121], v[190:193], v[14:17]
	v_mfma_f32_16x16x32_bf16 v[58:61], v[138:141], v[162:165], v[58:61]
	v_mfma_f32_16x16x32_bf16 v[58:61], v[142:145], v[166:169], v[58:61]
	v_mfma_f32_16x16x32_bf16 v[42:45], v[138:141], v[170:173], v[42:45]
	v_mfma_f32_16x16x32_bf16 v[42:45], v[142:145], v[174:177], v[42:45]
	v_mfma_f32_16x16x32_bf16 v[26:29], v[138:141], v[178:181], v[26:29]
	v_mfma_f32_16x16x32_bf16 v[26:29], v[142:145], v[182:185], v[26:29]
	v_mfma_f32_16x16x32_bf16 v[10:13], v[138:141], v[186:189], v[10:13]
	v_mfma_f32_16x16x32_bf16 v[10:13], v[142:145], v[190:193], v[10:13]
	v_mfma_f32_16x16x32_bf16 v[54:57], v[146:149], v[162:165], v[54:57]
	v_mfma_f32_16x16x32_bf16 v[54:57], v[150:153], v[166:169], v[54:57]
	v_mfma_f32_16x16x32_bf16 v[38:41], v[146:149], v[170:173], v[38:41]
	v_mfma_f32_16x16x32_bf16 v[38:41], v[150:153], v[174:177], v[38:41]
	v_mfma_f32_16x16x32_bf16 v[22:25], v[146:149], v[178:181], v[22:25]
	v_mfma_f32_16x16x32_bf16 v[22:25], v[150:153], v[182:185], v[22:25]
	v_mfma_f32_16x16x32_bf16 v[6:9], v[146:149], v[186:189], v[6:9]
	v_mfma_f32_16x16x32_bf16 v[6:9], v[150:153], v[190:193], v[6:9]
	v_mfma_f32_16x16x32_bf16 v[50:53], v[154:157], v[162:165], v[50:53]
	v_mfma_f32_16x16x32_bf16 v[50:53], v[158:161], v[166:169], v[50:53]
	v_mfma_f32_16x16x32_bf16 v[34:37], v[154:157], v[170:173], v[34:37]
	v_mfma_f32_16x16x32_bf16 v[34:37], v[158:161], v[174:177], v[34:37]
	v_mfma_f32_16x16x32_bf16 v[18:21], v[154:157], v[178:181], v[18:21]
	v_mfma_f32_16x16x32_bf16 v[18:21], v[158:161], v[182:185], v[18:21]
	v_mfma_f32_16x16x32_bf16 v[2:5], v[154:157], v[186:189], v[2:5]
	v_mfma_f32_16x16x32_bf16 v[2:5], v[158:161], v[190:193], v[2:5]
	s_setprio 0
	s_barrier
	s_add_u32 s48, s48, 0x100
	s_addc_u32 s49, s49, 0
	s_add_u32 s50, s50, 0x100
	s_addc_u32 s51, s51, 0
	s_cmp_ge_u32 vcc_lo, s96
	s_mov_b32 s46, vcc_lo
	s_cbranch_scc0 .LBB0_274
	s_and_b64 vcc, exec, s[72:73]
	s_cbranch_vccz .LBB0_277
	s_barrier

; #define PG8_STAGE(bufoff, gbase, voff) do { _Pragma("unroll") for (int _i = 0; _i < 2; ++_i) \
;         __builtin_amdgcn_global_load_lds((const unsigned*)((const char*)(gbase) + (voff)[_i]), (PG8_LAS unsigned*)(lds + (bufoff) + ldsw + _i * 8192), 16, 0, 0); } while (0)
; #define PG8_LDA(dst, b, h) do { _Pragma("unroll") for (int m = 0; m < 4; ++m) _Pragma("unroll") for (int k = 0; k < 2; ++k) dst[m][k] = *(const PG8_LAS bf16x8*)(lds + PG8_SA(b, h) + aoff + m * 2048 + k * 1024); } while (0)
; #define PG8_LDB(dst, b, h) do { _Pragma("unroll") for (int n = 0; n < 2; ++n) _Pragma("unroll") for (int k = 0; k < 2; ++k) dst[n][k] = *(const PG8_LAS bf16x8*)(lds + PG8_SB(b, h) + boff + n * 2048 + k * 1024); } while (0)
; #define PG8_MMA(ai, bj, At, Bt) do { __builtin_amdgcn_s_setprio(1); _Pragma("unroll") for (int m = 0; m < 4; ++m) _Pragma("unroll") for (int n = 0; n < 2; ++n) _Pragma("unroll") for (int k = 0; k < 2; ++k) \
;         acc[ai][bj][m][n] = __builtin_amdgcn_mfma_f32_16x16x32_bf16(Bt[n][k], At[m][k], acc[ai][bj][m][n], 0, 0, 0); __builtin_amdgcn_s_setprio(0); } while (0)
; #define PG8_WAIT_V(n) asm volatile("s_waitcnt vmcnt(" #n ")" ::: "memory")
; #define PG8_WAIT_L(n) asm volatile("s_waitcnt lgkmcnt(" #n ")" ::: "memory")
; #define PG8_BAR __builtin_amdgcn_s_barrier()
; #define PG8_SCHED __builtin_amdgcn_sched_barrier(0)
; template <class Epi, class Sched, bool ALIGN_EPI = false, bool SP2 = false>
; __device__ __forceinline__ void gemm_phase(PG8_LAS unsigned char* lds, const Gemm g, const Sched& S, const Epi& E) {
;     ...
;             PG8_LDB(B0, 0, 0); PG8_LDB(B1, 0, 1); PG8_SCHED; PG8_LDA(At, 0, 0); PG8_STAGE(PG8_SA(1, 1), a1 + hstep, voffA);
;             PG8_WAIT_V(8); PG8_WAIT_L(0); PG8_BAR; PG8_MMA(0, 0, At, B0); PG8_MMA(0, 1, At, B1); PG8_BAR; PG8_SCHED;
;             PG8_LDA(At, 0, 1); PG8_STAGE(PG8_SB(0, 0), b2, voffB); PG8_STAGE(PG8_SB(0, 1), b2 + hstep, voffB); PG8_STAGE(PG8_SA(0, 0), a2, voffA);
;             PG8_WAIT_V(8); PG8_WAIT_L(0); PG8_BAR; PG8_MMA(1, 0, At, B0); PG8_MMA(1, 1, At, B1); PG8_BAR; PG8_SCHED;
.LBB0_408:
	s_add_u32 s38, s48, 0xfffc0080
	s_addc_u32 s39, s49, -1
	s_add_i32 s85, 0, 0x10000
	s_cmp_eq_u32 s84, 12
	s_cselect_b32 s73, s21, s39
	s_cselect_b32 s72, s27, s38
	v_add_u32_e32 v0, s85, v167
	s_cselect_b32 s47, s29, s69
	s_cselect_b32 s46, s33, s53
	s_add_i32 s38, 0, 0x14000
	ds_read_b128 v[180:183], v170
	ds_read_b128 v[184:187], v170 offset:1024
	ds_read_b128 v[188:191], v170 offset:2048
	ds_read_b128 v[192:195], v170 offset:3072
	ds_read_b128 v[202:205], v170 offset:4096
	ds_read_b128 v[206:209], v170 offset:5120
	ds_read_b128 v[210:213], v170 offset:6144
	ds_read_b128 v[214:217], v170 offset:7168
	ds_read_b128 v[142:145], v0
	ds_read_b128 v[146:149], v0 offset:1024
	ds_read_b128 v[150:153], v0 offset:2048
	ds_read_b128 v[154:157], v0 offset:3072
	v_add_u32_e32 v0, s38, v167
	ds_read_b128 v[158:161], v0
	ds_read_b128 v[162:165], v0 offset:1024
	ds_read_b128 v[172:175], v0 offset:2048
	ds_read_b128 v[176:179], v0 offset:3072
	v_lshl_add_u64 v[218:219], s[48:49], 0, v[138:139]
	s_add_i32 m0, s76, 0xc000
	global_load_lds_dwordx4 v[218:219], off
	v_lshl_add_u64 v[218:219], s[48:49], 0, v[140:141]
	s_add_i32 m0, s76, 0xe000
	s_nop 0
	global_load_lds_dwordx4 v[218:219], off
	s_waitcnt vmcnt(8)
	s_waitcnt lgkmcnt(0)
	s_barrier
	s_setprio 1
	v_mfma_f32_16x16x32_bf16 v[122:125], v[142:145], v[180:183], v[122:125]
	v_mfma_f32_16x16x32_bf16 v[122:125], v[146:149], v[184:187], v[122:125]
	v_mfma_f32_16x16x32_bf16 v[106:109], v[142:145], v[188:191], v[106:109]
	v_mfma_f32_16x16x32_bf16 v[106:109], v[146:149], v[192:195], v[106:109]
	v_mfma_f32_16x16x32_bf16 v[90:93], v[142:145], v[202:205], v[90:93]
	v_mfma_f32_16x16x32_bf16 v[90:93], v[146:149], v[206:209], v[90:93]
	v_mfma_f32_16x16x32_bf16 v[74:77], v[142:145], v[210:213], v[74:77]
	v_mfma_f32_16x16x32_bf16 v[74:77], v[146:149], v[214:217], v[74:77]
	v_mfma_f32_16x16x32_bf16 v[126:129], v[150:153], v[180:183], v[126:129]
	v_mfma_f32_16x16x32_bf16 v[126:129], v[154:157], v[184:187], v[126:129]
	v_mfma_f32_16x16x32_bf16 v[110:113], v[150:153], v[188:191], v[110:113]
	v_mfma_f32_16x16x32_bf16 v[110:113], v[154:157], v[192:195], v[110:113]
	v_mfma_f32_16x16x32_bf16 v[94:97], v[150:153], v[202:205], v[94:97]
	v_mfma_f32_16x16x32_bf16 v[94:97], v[154:157], v[206:209], v[94:97]
	v_mfma_f32_16x16x32_bf16 v[78:81], v[150:153], v[210:213], v[78:81]
	v_mfma_f32_16x16x32_bf16 v[78:81], v[154:157], v[214:217], v[78:81]
	v_mfma_f32_16x16x32_bf16 v[114:117], v[158:161], v[180:183], v[114:117]
	v_mfma_f32_16x16x32_bf16 v[114:117], v[162:165], v[184:187], v[114:117]
	v_mfma_f32_16x16x32_bf16 v[98:101], v[158:161], v[188:191], v[98:101]
	v_mfma_f32_16x16x32_bf16 v[98:101], v[162:165], v[192:195], v[98:101]
	v_mfma_f32_16x16x32_bf16 v[82:85], v[158:161], v[202:205], v[82:85]
	v_mfma_f32_16x16x32_bf16 v[82:85], v[162:165], v[206:209], v[82:85]
	v_mfma_f32_16x16x32_bf16 v[66:69], v[158:161], v[210:213], v[66:69]
	v_mfma_f32_16x16x32_bf16 v[66:69], v[162:165], v[214:217], v[66:69]
	v_mfma_f32_16x16x32_bf16 v[118:121], v[172:175], v[180:183], v[118:121]
	v_mfma_f32_16x16x32_bf16 v[118:121], v[176:179], v[184:187], v[118:121]
	v_mfma_f32_16x16x32_bf16 v[102:105], v[172:175], v[188:191], v[102:105]
	v_mfma_f32_16x16x32_bf16 v[102:105], v[176:179], v[192:195], v[102:105]
	v_mfma_f32_16x16x32_bf16 v[86:89], v[172:175], v[202:205], v[86:89]
	v_mfma_f32_16x16x32_bf16 v[86:89], v[176:179], v[206:209], v[86:89]
	v_mfma_f32_16x16x32_bf16 v[70:73], v[172:175], v[210:213], v[70:73]
	v_mfma_f32_16x16x32_bf16 v[70:73], v[176:179], v[214:217], v[70:73]
	s_setprio 0
	s_barrier
	s_add_i32 s39, s85, s75
	v_lshl_add_u64 v[218:219], s[46:47], 0, v[134:135]
	s_mov_b32 m0, s39
	ds_read_b128 v[180:183], v170 offset:16384
	ds_read_b128 v[184:187], v170 offset:17408
	ds_read_b128 v[188:191], v170 offset:18432
	ds_read_b128 v[192:195], v170 offset:19456
	ds_read_b128 v[202:205], v170 offset:20480
	ds_read_b128 v[206:209], v170 offset:21504
	ds_read_b128 v[210:213], v170 offset:22528
	ds_read_b128 v[214:217], v170 offset:23552
	global_load_lds_dwordx4 v[218:219], off
	s_add_i32 m0, s39, 0x2000
	s_add_u32 s92, s46, 0x40000
	v_lshl_add_u64 v[220:221], s[46:47], 0, v[130:131]
	s_addc_u32 s93, s47, 0
	s_add_i32 s38, s38, s75
	global_load_lds_dwordx4 v[220:221], off
	v_lshl_add_u64 v[222:223], s[92:93], 0, v[134:135]
	s_mov_b32 m0, s38
	v_lshl_add_u64 v[224:225], s[72:73], 0, v[132:133]
	global_load_lds_dwordx4 v[222:223], off
	v_lshl_add_u64 v[222:223], s[92:93], 0, v[130:131]
	s_add_i32 m0, s38, 0x2000
	s_nop 0
	global_load_lds_dwordx4 v[222:223], off
	v_lshl_add_u64 v[222:223], s[72:73], 0, v[136:137]
	s_mov_b32 m0, s76
	s_nop 0
	global_load_lds_dwordx4 v[222:223], off
	s_mov_b32 m0, s77
	s_nop 0
	global_load_lds_dwordx4 v[224:225], off
	s_waitcnt vmcnt(8)
	s_waitcnt lgkmcnt(0)
	s_barrier
; #define PG8_STAGE(bufoff, gbase, voff) do { _Pragma("unroll") for (int _i = 0; _i < 2; ++_i) \
;         __builtin_amdgcn_global_load_lds((const unsigned*)((const char*)(gbase) + (voff)[_i]), (PG8_LAS unsigned*)(lds + (bufoff) + ldsw + _i * 8192), 16, 0, 0); } while (0)
; #define PG8_LDA(dst, b, h) do { _Pragma("unroll") for (int m = 0; m < 4; ++m) _Pragma("unroll") for (int k = 0; k < 2; ++k) dst[m][k] = *(const PG8_LAS bf16x8*)(lds + PG8_SA(b, h) + aoff + m * 2048 + k * 1024); } while (0)
; #define PG8_LDB(dst, b, h) do { _Pragma("unroll") for (int n = 0; n < 2; ++n) _Pragma("unroll") for (int k = 0; k < 2; ++k) dst[n][k] = *(const PG8_LAS bf16x8*)(lds + PG8_SB(b, h) + boff + n * 2048 + k * 1024); } while (0)
; #define PG8_MMA(ai, bj, At, Bt) do { __builtin_amdgcn_s_setprio(1); _Pragma("unroll") for (int m = 0; m < 4; ++m) _Pragma("unroll") for (int n = 0; n < 2; ++n) _Pragma("unroll") for (int k = 0; k < 2; ++k) \
;         acc[ai][bj][m][n] = __builtin_amdgcn_mfma_f32_16x16x32_bf16(Bt[n][k], At[m][k], acc[ai][bj][m][n], 0, 0, 0); __builtin_amdgcn_s_setprio(0); } while (0)
; #define PG8_WAIT_V(n) asm volatile("s_waitcnt vmcnt(" #n ")" ::: "memory")
; #define PG8_WAIT_L(n) asm volatile("s_waitcnt lgkmcnt(" #n ")" ::: "memory")
; #define PG8_BAR __builtin_amdgcn_s_barrier()
; #define PG8_SCHED __builtin_amdgcn_sched_barrier(0)
; template <class Epi, class Sched, bool ALIGN_EPI = false, bool SP2 = false>
; __device__ __forceinline__ void gemm_phase(PG8_LAS unsigned char* lds, const Gemm g, const Sched& S, const Epi& E) {
;     ...
;             PG8_WAIT_V(8); PG8_WAIT_L(0); PG8_BAR; PG8_MMA(1, 0, At, B0); PG8_MMA(1, 1, At, B1); PG8_BAR; PG8_SCHED;
;             PG8_LDB(B0, 1, 0); PG8_LDB(B1, 1, 1); PG8_SCHED; PG8_LDA(At, 1, 0); PG8_STAGE(PG8_SA(0, 1), a2 + hstep, voffA);
;             PG8_WAIT_V(8); PG8_WAIT_L(0); PG8_BAR; PG8_MMA(0, 0, At, B0); PG8_MMA(0, 1, At, B1); PG8_BAR; PG8_SCHED;
	s_setprio 1
	v_mfma_f32_16x16x32_bf16 v[58:61], v[142:145], v[180:183], v[58:61]
	v_mfma_f32_16x16x32_bf16 v[58:61], v[146:149], v[184:187], v[58:61]
	v_mfma_f32_16x16x32_bf16 v[42:45], v[142:145], v[188:191], v[42:45]
	v_mfma_f32_16x16x32_bf16 v[42:45], v[146:149], v[192:195], v[42:45]
	v_mfma_f32_16x16x32_bf16 v[26:29], v[142:145], v[202:205], v[26:29]
	v_mfma_f32_16x16x32_bf16 v[26:29], v[146:149], v[206:209], v[26:29]
	v_mfma_f32_16x16x32_bf16 v[10:13], v[142:145], v[210:213], v[10:13]
	v_mfma_f32_16x16x32_bf16 v[10:13], v[146:149], v[214:217], v[10:13]
	v_mfma_f32_16x16x32_bf16 v[62:65], v[150:153], v[180:183], v[62:65]
	v_mfma_f32_16x16x32_bf16 v[62:65], v[154:157], v[184:187], v[62:65]
	v_mfma_f32_16x16x32_bf16 v[46:49], v[150:153], v[188:191], v[46:49]
	v_mfma_f32_16x16x32_bf16 v[46:49], v[154:157], v[192:195], v[46:49]
	v_mfma_f32_16x16x32_bf16 v[30:33], v[150:153], v[202:205], v[30:33]
	v_mfma_f32_16x16x32_bf16 v[30:33], v[154:157], v[206:209], v[30:33]
	v_mfma_f32_16x16x32_bf16 v[14:17], v[150:153], v[210:213], v[14:17]
	v_mfma_f32_16x16x32_bf16 v[14:17], v[154:157], v[214:217], v[14:17]
	v_mfma_f32_16x16x32_bf16 v[50:53], v[158:161], v[180:183], v[50:53]
	v_mfma_f32_16x16x32_bf16 v[50:53], v[162:165], v[184:187], v[50:53]
	v_mfma_f32_16x16x32_bf16 v[34:37], v[158:161], v[188:191], v[34:37]
	v_mfma_f32_16x16x32_bf16 v[34:37], v[162:165], v[192:195], v[34:37]
	v_mfma_f32_16x16x32_bf16 v[18:21], v[158:161], v[202:205], v[18:21]
	v_mfma_f32_16x16x32_bf16 v[18:21], v[162:165], v[206:209], v[18:21]
	v_mfma_f32_16x16x32_bf16 v[2:5], v[158:161], v[210:213], v[2:5]
	v_mfma_f32_16x16x32_bf16 v[2:5], v[162:165], v[214:217], v[2:5]
	v_mfma_f32_16x16x32_bf16 v[54:57], v[172:175], v[180:183], v[54:57]
	v_mfma_f32_16x16x32_bf16 v[54:57], v[176:179], v[184:187], v[54:57]
	v_mfma_f32_16x16x32_bf16 v[38:41], v[172:175], v[188:191], v[38:41]
	v_mfma_f32_16x16x32_bf16 v[38:41], v[176:179], v[192:195], v[38:41]
	v_mfma_f32_16x16x32_bf16 v[22:25], v[172:175], v[202:205], v[22:25]
	v_mfma_f32_16x16x32_bf16 v[22:25], v[176:179], v[206:209], v[22:25]
	v_mfma_f32_16x16x32_bf16 v[6:9], v[172:175], v[210:213], v[6:9]
	v_mfma_f32_16x16x32_bf16 v[6:9], v[176:179], v[214:217], v[6:9]
	s_setprio 0
	s_barrier
	s_add_i32 s38, 0, 0x18000
	v_add_u32_e32 v0, s38, v167
	s_add_i32 s39, 0, 0x1c000
	ds_read_b128 v[180:183], v170 offset:32768
	ds_read_b128 v[184:187], v170 offset:33792
	ds_read_b128 v[188:191], v170 offset:34816
	ds_read_b128 v[192:195], v170 offset:35840
	ds_read_b128 v[202:205], v170 offset:36864
	ds_read_b128 v[206:209], v170 offset:37888
	ds_read_b128 v[210:213], v170 offset:38912
	ds_read_b128 v[214:217], v170 offset:39936
	ds_read_b128 v[142:145], v0
	ds_read_b128 v[146:149], v0 offset:1024
	ds_read_b128 v[150:153], v0 offset:2048
	ds_read_b128 v[154:157], v0 offset:3072
	v_add_u32_e32 v0, s39, v167
	ds_read_b128 v[158:161], v0
	ds_read_b128 v[162:165], v0 offset:1024
	ds_read_b128 v[172:175], v0 offset:2048
	ds_read_b128 v[176:179], v0 offset:3072
	s_add_u32 s72, s72, 0x40000
	s_addc_u32 s73, s73, 0
	s_mov_b32 m0, s78
	v_lshl_add_u64 v[226:227], s[72:73], 0, v[136:137]
	global_load_lds_dwordx4 v[226:227], off
	v_lshl_add_u64 v[226:227], s[72:73], 0, v[132:133]
	s_mov_b32 m0, s79
	s_nop 0
	global_load_lds_dwordx4 v[226:227], off
	s_waitcnt vmcnt(8)
	s_waitcnt lgkmcnt(0)
	s_barrier
	s_setprio 1
	v_mfma_f32_16x16x32_bf16 v[122:125], v[142:145], v[180:183], v[122:125]
	v_mfma_f32_16x16x32_bf16 v[122:125], v[146:149], v[184:187], v[122:125]
	v_mfma_f32_16x16x32_bf16 v[106:109], v[142:145], v[188:191], v[106:109]
	v_mfma_f32_16x16x32_bf16 v[106:109], v[146:149], v[192:195], v[106:109]
	v_mfma_f32_16x16x32_bf16 v[90:93], v[142:145], v[202:205], v[90:93]
	v_mfma_f32_16x16x32_bf16 v[90:93], v[146:149], v[206:209], v[90:93]
	v_mfma_f32_16x16x32_bf16 v[74:77], v[142:145], v[210:213], v[74:77]
	v_mfma_f32_16x16x32_bf16 v[74:77], v[146:149], v[214:217], v[74:77]
	v_mfma_f32_16x16x32_bf16 v[126:129], v[150:153], v[180:183], v[126:129]
	v_mfma_f32_16x16x32_bf16 v[126:129], v[154:157], v[184:187], v[126:129]
	v_mfma_f32_16x16x32_bf16 v[110:113], v[150:153], v[188:191], v[110:113]
	v_mfma_f32_16x16x32_bf16 v[110:113], v[154:157], v[192:195], v[110:113]
	v_mfma_f32_16x16x32_bf16 v[94:97], v[150:153], v[202:205], v[94:97]
	v_mfma_f32_16x16x32_bf16 v[94:97], v[154:157], v[206:209], v[94:97]
	v_mfma_f32_16x16x32_bf16 v[78:81], v[150:153], v[210:213], v[78:81]
	v_mfma_f32_16x16x32_bf16 v[78:81], v[154:157], v[214:217], v[78:81]
	v_mfma_f32_16x16x32_bf16 v[114:117], v[158:161], v[180:183], v[114:117]
	v_mfma_f32_16x16x32_bf16 v[114:117], v[162:165], v[184:187], v[114:117]
	v_mfma_f32_16x16x32_bf16 v[98:101], v[158:161], v[188:191], v[98:101]
	v_mfma_f32_16x16x32_bf16 v[98:101], v[162:165], v[192:195], v[98:101]
	v_mfma_f32_16x16x32_bf16 v[82:85], v[158:161], v[202:205], v[82:85]
	v_mfma_f32_16x16x32_bf16 v[82:85], v[162:165], v[206:209], v[82:85]
	v_mfma_f32_16x16x32_bf16 v[66:69], v[158:161], v[210:213], v[66:69]
	v_mfma_f32_16x16x32_bf16 v[66:69], v[162:165], v[214:217], v[66:69]
	v_mfma_f32_16x16x32_bf16 v[118:121], v[172:175], v[180:183], v[118:121]
	v_mfma_f32_16x16x32_bf16 v[118:121], v[176:179], v[184:187], v[118:121]
	v_mfma_f32_16x16x32_bf16 v[102:105], v[172:175], v[188:191], v[102:105]
	v_mfma_f32_16x16x32_bf16 v[102:105], v[176:179], v[192:195], v[102:105]
	v_mfma_f32_16x16x32_bf16 v[86:89], v[172:175], v[202:205], v[86:89]
	v_mfma_f32_16x16x32_bf16 v[86:89], v[176:179], v[206:209], v[86:89]
	v_mfma_f32_16x16x32_bf16 v[70:73], v[172:175], v[210:213], v[70:73]
	v_mfma_f32_16x16x32_bf16 v[70:73], v[176:179], v[214:217], v[70:73]
	s_setprio 0
	s_barrier
; #define PG8_STAGE(bufoff, gbase, voff) do { _Pragma("unroll") for (int _i = 0; _i < 2; ++_i) \
;         __builtin_amdgcn_global_load_lds((const unsigned*)((const char*)(gbase) + (voff)[_i]), (PG8_LAS unsigned*)(lds + (bufoff) + ldsw + _i * 8192), 16, 0, 0); } while (0)
; #define PG8_LDA(dst, b, h) do { _Pragma("unroll") for (int m = 0; m < 4; ++m) _Pragma("unroll") for (int k = 0; k < 2; ++k) dst[m][k] = *(const PG8_LAS bf16x8*)(lds + PG8_SA(b, h) + aoff + m * 2048 + k * 1024); } while (0)
; #define PG8_MMA(ai, bj, At, Bt) do { __builtin_amdgcn_s_setprio(1); _Pragma("unroll") for (int m = 0; m < 4; ++m) _Pragma("unroll") for (int n = 0; n < 2; ++n) _Pragma("unroll") for (int k = 0; k < 2; ++k) \
;         acc[ai][bj][m][n] = __builtin_amdgcn_mfma_f32_16x16x32_bf16(Bt[n][k], At[m][k], acc[ai][bj][m][n], 0, 0, 0); __builtin_amdgcn_s_setprio(0); } while (0)
; #define PG8_WAIT_V(n) asm volatile("s_waitcnt vmcnt(" #n ")" ::: "memory")
; #define PG8_WAIT_L(n) asm volatile("s_waitcnt lgkmcnt(" #n ")" ::: "memory")
; #define PG8_BAR __builtin_amdgcn_s_barrier()
; #define PG8_SCHED __builtin_amdgcn_sched_barrier(0)
; template <class Epi, class Sched, bool ALIGN_EPI = false, bool SP2 = false>
; __device__ __forceinline__ void gemm_phase(PG8_LAS unsigned char* lds, const Gemm g, const Sched& S, const Epi& E) {
;     ...
;         for (int t = 0; t < nt; t += 2) {
;             const bool last = (t == nt - 2);
;     ...
;             PG8_LDA(At, 1, 1); PG8_STAGE(PG8_SB(1, 0), b3, voffB); PG8_STAGE(PG8_SB(1, 1), b3 + hstep, voffB); PG8_STAGE(PG8_SA(1, 0), a3, voffA);
;             PG8_WAIT_V(8); PG8_WAIT_L(0); PG8_BAR; PG8_MMA(1, 0, At, B0); PG8_MMA(1, 1, At, B1); PG8_BAR; PG8_SCHED;
	s_add_i32 s38, s38, s75
	v_lshl_add_u64 v[218:219], v[218:219], 0, s[30:31]
	s_mov_b32 m0, s38
	ds_read_b128 v[180:183], v170 offset:49152
	ds_read_b128 v[184:187], v170 offset:50176
	ds_read_b128 v[188:191], v170 offset:51200
	ds_read_b128 v[192:195], v170 offset:52224
	ds_read_b128 v[202:205], v170 offset:53248
	ds_read_b128 v[206:209], v170 offset:54272
	ds_read_b128 v[210:213], v170 offset:55296
	ds_read_b128 v[214:217], v170 offset:56320
	global_load_lds_dwordx4 v[218:219], off
	s_add_i32 m0, s38, 0x2000
	s_add_u32 s46, s46, 0x40080
	v_lshl_add_u64 v[218:219], v[220:221], 0, s[30:31]
	s_addc_u32 s47, s47, 0
	s_add_i32 s38, s39, s75
	global_load_lds_dwordx4 v[218:219], off
	v_lshl_add_u64 v[218:219], s[46:47], 0, v[134:135]
	s_mov_b32 m0, s38
	s_nop 0
	global_load_lds_dwordx4 v[218:219], off
	v_lshl_add_u64 v[218:219], s[46:47], 0, v[130:131]
	s_add_i32 m0, s38, 0x2000
	s_nop 0
	global_load_lds_dwordx4 v[218:219], off
	v_lshl_add_u64 v[218:219], v[222:223], 0, s[30:31]
	s_mov_b32 m0, s80
	s_nop 0
	global_load_lds_dwordx4 v[218:219], off
	v_lshl_add_u64 v[218:219], v[224:225], 0, s[30:31]
	s_mov_b32 m0, s81
	s_nop 0
	global_load_lds_dwordx4 v[218:219], off
	s_waitcnt vmcnt(8)
	s_waitcnt lgkmcnt(0)
	s_barrier
	s_setprio 1
	v_mfma_f32_16x16x32_bf16 v[58:61], v[142:145], v[180:183], v[58:61]
	v_mfma_f32_16x16x32_bf16 v[58:61], v[146:149], v[184:187], v[58:61]
	v_mfma_f32_16x16x32_bf16 v[42:45], v[142:145], v[188:191], v[42:45]
	v_mfma_f32_16x16x32_bf16 v[42:45], v[146:149], v[192:195], v[42:45]
	v_mfma_f32_16x16x32_bf16 v[26:29], v[142:145], v[202:205], v[26:29]
	v_mfma_f32_16x16x32_bf16 v[26:29], v[146:149], v[206:209], v[26:29]
	v_mfma_f32_16x16x32_bf16 v[10:13], v[142:145], v[210:213], v[10:13]
	v_mfma_f32_16x16x32_bf16 v[10:13], v[146:149], v[214:217], v[10:13]
	v_mfma_f32_16x16x32_bf16 v[62:65], v[150:153], v[180:183], v[62:65]
	v_mfma_f32_16x16x32_bf16 v[62:65], v[154:157], v[184:187], v[62:65]
	v_mfma_f32_16x16x32_bf16 v[46:49], v[150:153], v[188:191], v[46:49]
	v_mfma_f32_16x16x32_bf16 v[46:49], v[154:157], v[192:195], v[46:49]
	v_mfma_f32_16x16x32_bf16 v[30:33], v[150:153], v[202:205], v[30:33]
	v_mfma_f32_16x16x32_bf16 v[30:33], v[154:157], v[206:209], v[30:33]
	v_mfma_f32_16x16x32_bf16 v[14:17], v[150:153], v[210:213], v[14:17]
	v_mfma_f32_16x16x32_bf16 v[14:17], v[154:157], v[214:217], v[14:17]
	v_mfma_f32_16x16x32_bf16 v[50:53], v[158:161], v[180:183], v[50:53]
	v_mfma_f32_16x16x32_bf16 v[50:53], v[162:165], v[184:187], v[50:53]
	v_mfma_f32_16x16x32_bf16 v[34:37], v[158:161], v[188:191], v[34:37]
	v_mfma_f32_16x16x32_bf16 v[34:37], v[162:165], v[192:195], v[34:37]
	v_mfma_f32_16x16x32_bf16 v[18:21], v[158:161], v[202:205], v[18:21]
	v_mfma_f32_16x16x32_bf16 v[18:21], v[162:165], v[206:209], v[18:21]
	v_mfma_f32_16x16x32_bf16 v[2:5], v[158:161], v[210:213], v[2:5]
	v_mfma_f32_16x16x32_bf16 v[2:5], v[162:165], v[214:217], v[2:5]
	v_mfma_f32_16x16x32_bf16 v[54:57], v[172:175], v[180:183], v[54:57]
	v_mfma_f32_16x16x32_bf16 v[54:57], v[176:179], v[184:187], v[54:57]
	v_mfma_f32_16x16x32_bf16 v[38:41], v[172:175], v[188:191], v[38:41]
	v_mfma_f32_16x16x32_bf16 v[38:41], v[176:179], v[192:195], v[38:41]
	v_mfma_f32_16x16x32_bf16 v[22:25], v[172:175], v[202:205], v[22:25]
	v_mfma_f32_16x16x32_bf16 v[22:25], v[176:179], v[206:209], v[22:25]
	v_mfma_f32_16x16x32_bf16 v[6:9], v[172:175], v[210:213], v[6:9]
	v_mfma_f32_16x16x32_bf16 v[6:9], v[176:179], v[214:217], v[6:9]
	s_setprio 0
	s_barrier
	s_add_i32 s84, s84, 2
	s_add_u32 s48, s48, 0x100
	s_addc_u32 s49, s49, 0
	s_add_u32 s53, s53, 0x100
	s_addc_u32 s69, s69, 0
	s_cmp_gt_u32 s84, 13
	s_cbranch_scc0 .LBB0_408
	s_and_b64 vcc, exec, s[64:65]
	s_cbranch_vccz .LBB0_411
	s_barrier
